# 16x16x32 GEMM loops: LDS staging writes of the next slab moved earlier (into the second half of k-step 0 and first half of k-step 1) so the end-of-slab lgkmcnt(0) does not wait on them
# speedup vs baseline: 1.0100x; 1.0022x over previous
; #define MFMA(a, b, c) __builtin_amdgcn_mfma_f32_32x32x16_bf16((a), (b), (c), 0, 0, 0)
; template <bool SWAP, class Epi>
; DI void gemm_tile(const u16* __restrict__ A, int lda, const u16* __restrict__ Bt, int ldb, int K, int m0, int n0, char* smem, Epi&& epi) {
;     ...
;   auto compute = [&](int buf) __attribute__((always_inline)) {
;     bf16x8 af[2][2], bfr[2][2];
;     af[0][0] = *(const bf16x8*)(Asb + buf * 128 * 72);
;     af[0][1] = *(const bf16x8*)(Asb + buf * 128 * 72 + 32 * 72);
;     bfr[0][0] = *(const bf16x8*)(Bsb + buf * 128 * 72);
;     bfr[0][1] = *(const bf16x8*)(Bsb + buf * 128 * 72 + 32 * 72);
; #pragma unroll
;     for (int ks = 0; ks < 4; ++ks) {
;       const int c = ks & 1, n = c ^ 1;
;       if (ks < 3) {
;         af[n][0] = *(const bf16x8*)(Asb + buf * 128 * 72 + (ks + 1) * 16);
;         af[n][1] = *(const bf16x8*)(Asb + buf * 128 * 72 + 32 * 72 + (ks + 1) * 16);
;         bfr[n][0] = *(const bf16x8*)(Bsb + buf * 128 * 72 + (ks + 1) * 16);
;         bfr[n][1] = *(const bf16x8*)(Bsb + buf * 128 * 72 + 32 * 72 + (ks + 1) * 16);
;       }
;       __builtin_amdgcn_sched_barrier(0);
; #pragma unroll
;       for (int mi = 0; mi < 2; ++mi)
; #pragma unroll
;         for (int ni = 0; ni < 2; ++ni) {
;           if (SWAP) acc[mi][ni] = MFMA(bfr[c][ni], af[c][mi], acc[mi][ni]);
;           else acc[mi][ni] = MFMA(af[c][mi], bfr[c][ni], acc[mi][ni]);
;         }
;       __builtin_amdgcn_sched_barrier(0);
;     }
;   };
;   for (int kt = 0; kt < KT; kt += 2) {
;     if (kt + 2 < KT) {
;       const int k0 = (kt + 2) << 6;
; #pragma unroll
;       for (int i = 0; i < 4; ++i) { ra0[i] = *(const u32x4*)(ag + (size_t)i * 32 * lda + k0); rb0[i] = *(const u32x4*)(bg + (size_t)i * 32 * ldb + k0); }
;     }
;     compute(0);
; #pragma unroll
;     for (int i = 0; i < 4; ++i) { *(u32x4*)(asw + 128 * 72 + 32 * i * 72) = ra1[i]; *(u32x4*)(bsw + 128 * 72 + 32 * i * 72) = rb1[i]; }
;     __syncthreads();
;     if (kt + 3 < KT) {
;       const int k0 = (kt + 3) << 6;
; #pragma unroll
;       for (int i = 0; i < 4; ++i) { ra1[i] = *(const u32x4*)(ag + (size_t)i * 32 * lda + k0); rb1[i] = *(const u32x4*)(bg + (size_t)i * 32 * ldb + k0); }
;     }
;     compute(1);
;     if (kt + 2 < KT) {
; #pragma unroll
;       for (int i = 0; i < 4; ++i) { *(u32x4*)(asw + 32 * i * 72) = ra0[i]; *(u32x4*)(bsw + 32 * i * 72) = rb0[i]; }
;     }
;     __syncthreads();
;   }
.LBB0_387:
	global_load_dwordx4 v[66:69], v194, s[100:101] offset:256
	global_load_dwordx4 v[70:73], v190, s[98:99] offset:256
	global_load_dwordx4 v[74:77], v195, s[100:101] offset:256
	global_load_dwordx4 v[78:81], v191, s[98:99] offset:256
	global_load_dwordx4 v[82:85], v196, s[100:101] offset:256
	global_load_dwordx4 v[86:89], v192, s[98:99] offset:256
	global_load_dwordx4 v[90:93], v197, s[100:101] offset:256
	global_load_dwordx4 v[94:97], v193, s[98:99] offset:256
	ds_read_b128 v[170:173], v150 offset:36880
	ds_read_b128 v[154:157], v149 offset:16
	ds_read_b128 v[158:161], v149 offset:2320
	ds_read_b128 v[174:177], v150 offset:39184
	ds_read_b128 v[162:165], v149 offset:4624
	ds_read_b128 v[166:169], v149 offset:6928
	ds_read_b128 v[178:181], v150 offset:41488
	ds_read_b128 v[182:185], v150 offset:43792
	s_waitcnt lgkmcnt(6)
	v_mfma_f32_16x16x32_bf16 v[50:53], v[170:173], v[154:157], v[50:53]
	s_waitcnt lgkmcnt(5)
	v_mfma_f32_16x16x32_bf16 v[54:57], v[170:173], v[158:161], v[54:57]
	s_waitcnt lgkmcnt(4)
	v_mfma_f32_16x16x32_bf16 v[58:61], v[174:177], v[154:157], v[58:61]
	v_mfma_f32_16x16x32_bf16 v[62:65], v[174:177], v[158:161], v[62:65]
	ds_read_b128 v[214:217], v150 offset:36944
	ds_read_b128 v[198:201], v149 offset:80
	ds_read_b128 v[202:205], v149 offset:2384
	ds_read_b128 v[218:221], v150 offset:39248
	s_waitcnt lgkmcnt(7)
	v_mfma_f32_16x16x32_bf16 v[18:21], v[170:173], v[162:165], v[18:21]
	v_mfma_f32_16x16x32_bf16 v[26:29], v[174:177], v[162:165], v[26:29]
	s_waitcnt lgkmcnt(6)
	v_mfma_f32_16x16x32_bf16 v[22:25], v[170:173], v[166:169], v[22:25]
	v_mfma_f32_16x16x32_bf16 v[30:33], v[174:177], v[166:169], v[30:33]
	ds_read_b128 v[206:209], v149 offset:4688
	ds_read_b128 v[210:213], v149 offset:6992
	ds_read_b128 v[222:225], v150 offset:41552
	ds_read_b128 v[226:229], v150 offset:43856
	s_waitcnt lgkmcnt(9)
	v_mfma_f32_16x16x32_bf16 v[34:37], v[178:181], v[154:157], v[34:37]
	v_mfma_f32_16x16x32_bf16 v[38:41], v[178:181], v[158:161], v[38:41]
	s_waitcnt vmcnt(14)
	ds_write_b128 v146, v[98:101] offset:18448
	ds_write_b128 v146, v[102:105] offset:55312
	v_mfma_f32_16x16x32_bf16 v[2:5], v[178:181], v[162:165], v[2:5]
	v_mfma_f32_16x16x32_bf16 v[6:9], v[178:181], v[166:169], v[6:9]
	s_waitcnt lgkmcnt(10)
	v_mfma_f32_16x16x32_bf16 v[42:45], v[182:185], v[154:157], v[42:45]
	v_mfma_f32_16x16x32_bf16 v[46:49], v[182:185], v[158:161], v[46:49]
	s_waitcnt vmcnt(12)
	ds_write_b128 v146, v[106:109] offset:23056
	ds_write_b128 v146, v[110:113] offset:59920
	v_mfma_f32_16x16x32_bf16 v[10:13], v[182:185], v[162:165], v[10:13]
	v_mfma_f32_16x16x32_bf16 v[14:17], v[182:185], v[166:169], v[14:17]
	s_waitcnt lgkmcnt(10)
	v_mfma_f32_16x16x32_bf16 v[50:53], v[214:217], v[198:201], v[50:53]
	s_waitcnt lgkmcnt(9)
	v_mfma_f32_16x16x32_bf16 v[54:57], v[214:217], v[202:205], v[54:57]
	s_waitcnt vmcnt(10)
	ds_write_b128 v146, v[114:117] offset:27664
	ds_write_b128 v146, v[118:121] offset:64528
	s_waitcnt lgkmcnt(10)
	v_mfma_f32_16x16x32_bf16 v[58:61], v[218:221], v[198:201], v[58:61]
	v_mfma_f32_16x16x32_bf16 v[62:65], v[218:221], v[202:205], v[62:65]
	s_waitcnt lgkmcnt(9)
	v_mfma_f32_16x16x32_bf16 v[18:21], v[214:217], v[206:209], v[18:21]
	v_mfma_f32_16x16x32_bf16 v[26:29], v[218:221], v[206:209], v[26:29]
	s_waitcnt vmcnt(8)
	ds_write_b128 v146, v[122:125] offset:32272
	ds_write_b128 v147, v[126:129] offset:32256
	s_waitcnt lgkmcnt(10)
	v_mfma_f32_16x16x32_bf16 v[22:25], v[214:217], v[210:213], v[22:25]
	v_mfma_f32_16x16x32_bf16 v[30:33], v[218:221], v[210:213], v[30:33]
	s_waitcnt lgkmcnt(9)
	v_mfma_f32_16x16x32_bf16 v[34:37], v[222:225], v[198:201], v[34:37]
	v_mfma_f32_16x16x32_bf16 v[38:41], v[222:225], v[202:205], v[38:41]
	v_mfma_f32_16x16x32_bf16 v[2:5], v[222:225], v[206:209], v[2:5]
	v_mfma_f32_16x16x32_bf16 v[6:9], v[222:225], v[210:213], v[6:9]
	s_waitcnt lgkmcnt(8)
	v_mfma_f32_16x16x32_bf16 v[42:45], v[226:229], v[198:201], v[42:45]
	v_mfma_f32_16x16x32_bf16 v[46:49], v[226:229], v[202:205], v[46:49]
	v_mfma_f32_16x16x32_bf16 v[10:13], v[226:229], v[206:209], v[10:13]
	v_mfma_f32_16x16x32_bf16 v[14:17], v[226:229], v[210:213], v[14:17]
	s_waitcnt lgkmcnt(0)
	s_barrier
	global_load_dwordx4 v[98:101], v194, s[100:101] offset:384
	global_load_dwordx4 v[102:105], v190, s[98:99] offset:384
	global_load_dwordx4 v[106:109], v195, s[100:101] offset:384
	global_load_dwordx4 v[110:113], v191, s[98:99] offset:384
	global_load_dwordx4 v[114:117], v196, s[100:101] offset:384
	global_load_dwordx4 v[118:121], v192, s[98:99] offset:384
	global_load_dwordx4 v[122:125], v197, s[100:101] offset:384
	global_load_dwordx4 v[126:129], v193, s[98:99] offset:384
	ds_read_b128 v[170:173], v150 offset:55312
	ds_read_b128 v[154:157], v149 offset:18448
	ds_read_b128 v[158:161], v149 offset:20752
	ds_read_b128 v[174:177], v150 offset:57616
	ds_read_b128 v[162:165], v149 offset:23056
	ds_read_b128 v[166:169], v149 offset:25360
	ds_read_b128 v[178:181], v150 offset:59920
	ds_read_b128 v[182:185], v150 offset:62224
	s_waitcnt lgkmcnt(6)
	v_mfma_f32_16x16x32_bf16 v[50:53], v[170:173], v[154:157], v[50:53]
	s_waitcnt lgkmcnt(5)
	v_mfma_f32_16x16x32_bf16 v[54:57], v[170:173], v[158:161], v[54:57]
	s_waitcnt lgkmcnt(4)
	v_mfma_f32_16x16x32_bf16 v[58:61], v[174:177], v[154:157], v[58:61]
	v_mfma_f32_16x16x32_bf16 v[62:65], v[174:177], v[158:161], v[62:65]
	ds_read_b128 v[214:217], v150 offset:55376
	ds_read_b128 v[198:201], v149 offset:18512
	ds_read_b128 v[202:205], v149 offset:20816
	ds_read_b128 v[218:221], v150 offset:57680
	s_waitcnt lgkmcnt(7)
	v_mfma_f32_16x16x32_bf16 v[18:21], v[170:173], v[162:165], v[18:21]
	v_mfma_f32_16x16x32_bf16 v[26:29], v[174:177], v[162:165], v[26:29]
	s_waitcnt lgkmcnt(6)
; #define MFMA(a, b, c) __builtin_amdgcn_mfma_f32_32x32x16_bf16((a), (b), (c), 0, 0, 0)
; template <bool SWAP, class Epi>
; DI void gemm_tile(const u16* __restrict__ A, int lda, const u16* __restrict__ Bt, int ldb, int K, int m0, int n0, char* smem, Epi&& epi) {
;     ...
;   auto compute = [&](int buf) __attribute__((always_inline)) {
;     bf16x8 af[2][2], bfr[2][2];
;     af[0][0] = *(const bf16x8*)(Asb + buf * 128 * 72);
;     af[0][1] = *(const bf16x8*)(Asb + buf * 128 * 72 + 32 * 72);
;     bfr[0][0] = *(const bf16x8*)(Bsb + buf * 128 * 72);
;     bfr[0][1] = *(const bf16x8*)(Bsb + buf * 128 * 72 + 32 * 72);
; #pragma unroll
;     for (int ks = 0; ks < 4; ++ks) {
;       const int c = ks & 1, n = c ^ 1;
;       if (ks < 3) {
;         af[n][0] = *(const bf16x8*)(Asb + buf * 128 * 72 + (ks + 1) * 16);
;         af[n][1] = *(const bf16x8*)(Asb + buf * 128 * 72 + 32 * 72 + (ks + 1) * 16);
;         bfr[n][0] = *(const bf16x8*)(Bsb + buf * 128 * 72 + (ks + 1) * 16);
;         bfr[n][1] = *(const bf16x8*)(Bsb + buf * 128 * 72 + 32 * 72 + (ks + 1) * 16);
;       }
;       __builtin_amdgcn_sched_barrier(0);
; #pragma unroll
;       for (int mi = 0; mi < 2; ++mi)
; #pragma unroll
;         for (int ni = 0; ni < 2; ++ni) {
;           if (SWAP) acc[mi][ni] = MFMA(bfr[c][ni], af[c][mi], acc[mi][ni]);
;           else acc[mi][ni] = MFMA(af[c][mi], bfr[c][ni], acc[mi][ni]);
;         }
;       __builtin_amdgcn_sched_barrier(0);
;     }
;   };
;   for (int kt = 0; kt < KT; kt += 2) {
;     if (kt + 2 < KT) {
;       const int k0 = (kt + 2) << 6;
; #pragma unroll
;       for (int i = 0; i < 4; ++i) { ra0[i] = *(const u32x4*)(ag + (size_t)i * 32 * lda + k0); rb0[i] = *(const u32x4*)(bg + (size_t)i * 32 * ldb + k0); }
;     }
;     compute(0);
; #pragma unroll
;     for (int i = 0; i < 4; ++i) { *(u32x4*)(asw + 128 * 72 + 32 * i * 72) = ra1[i]; *(u32x4*)(bsw + 128 * 72 + 32 * i * 72) = rb1[i]; }
;     __syncthreads();
;     if (kt + 3 < KT) {
;       const int k0 = (kt + 3) << 6;
; #pragma unroll
;       for (int i = 0; i < 4; ++i) { ra1[i] = *(const u32x4*)(ag + (size_t)i * 32 * lda + k0); rb1[i] = *(const u32x4*)(bg + (size_t)i * 32 * ldb + k0); }
;     }
;     compute(1);
;     if (kt + 2 < KT) {
; #pragma unroll
;       for (int i = 0; i < 4; ++i) { *(u32x4*)(asw + 32 * i * 72) = ra0[i]; *(u32x4*)(bsw + 32 * i * 72) = rb0[i]; }
;     }
;     __syncthreads();
;   }
	v_mfma_f32_16x16x32_bf16 v[22:25], v[170:173], v[166:169], v[22:25]
	v_mfma_f32_16x16x32_bf16 v[30:33], v[174:177], v[166:169], v[30:33]
	ds_read_b128 v[206:209], v149 offset:23120
	ds_read_b128 v[210:213], v149 offset:25424
	ds_read_b128 v[222:225], v150 offset:59984
	ds_read_b128 v[226:229], v150 offset:62288
	s_waitcnt lgkmcnt(9)
	v_mfma_f32_16x16x32_bf16 v[34:37], v[178:181], v[154:157], v[34:37]
	v_mfma_f32_16x16x32_bf16 v[38:41], v[178:181], v[158:161], v[38:41]
	s_waitcnt vmcnt(14)
	ds_write_b128 v146, v[66:69] offset:16
	ds_write_b128 v146, v[70:73] offset:36880
	v_mfma_f32_16x16x32_bf16 v[2:5], v[178:181], v[162:165], v[2:5]
	v_mfma_f32_16x16x32_bf16 v[6:9], v[178:181], v[166:169], v[6:9]
	s_waitcnt lgkmcnt(10)
	v_mfma_f32_16x16x32_bf16 v[42:45], v[182:185], v[154:157], v[42:45]
	v_mfma_f32_16x16x32_bf16 v[46:49], v[182:185], v[158:161], v[46:49]
	s_waitcnt vmcnt(12)
	ds_write_b128 v146, v[74:77] offset:4624
	ds_write_b128 v146, v[78:81] offset:41488
	v_mfma_f32_16x16x32_bf16 v[10:13], v[182:185], v[162:165], v[10:13]
	v_mfma_f32_16x16x32_bf16 v[14:17], v[182:185], v[166:169], v[14:17]
	s_waitcnt lgkmcnt(10)
	v_mfma_f32_16x16x32_bf16 v[50:53], v[214:217], v[198:201], v[50:53]
	s_waitcnt lgkmcnt(9)
	v_mfma_f32_16x16x32_bf16 v[54:57], v[214:217], v[202:205], v[54:57]
	s_waitcnt vmcnt(10)
	ds_write_b128 v146, v[82:85] offset:9232
	ds_write_b128 v146, v[86:89] offset:46096
	s_waitcnt lgkmcnt(10)
	v_mfma_f32_16x16x32_bf16 v[58:61], v[218:221], v[198:201], v[58:61]
	v_mfma_f32_16x16x32_bf16 v[62:65], v[218:221], v[202:205], v[62:65]
	s_waitcnt lgkmcnt(9)
	v_mfma_f32_16x16x32_bf16 v[18:21], v[214:217], v[206:209], v[18:21]
	v_mfma_f32_16x16x32_bf16 v[26:29], v[218:221], v[206:209], v[26:29]
	s_waitcnt vmcnt(8)
	ds_write_b128 v146, v[90:93] offset:13840
	ds_write_b128 v146, v[94:97] offset:50704
	s_waitcnt lgkmcnt(10)
	v_mfma_f32_16x16x32_bf16 v[22:25], v[214:217], v[210:213], v[22:25]
	v_mfma_f32_16x16x32_bf16 v[30:33], v[218:221], v[210:213], v[30:33]
	s_waitcnt lgkmcnt(9)
	v_mfma_f32_16x16x32_bf16 v[34:37], v[222:225], v[198:201], v[34:37]
	v_mfma_f32_16x16x32_bf16 v[38:41], v[222:225], v[202:205], v[38:41]
	v_mfma_f32_16x16x32_bf16 v[2:5], v[222:225], v[206:209], v[2:5]
	v_mfma_f32_16x16x32_bf16 v[6:9], v[222:225], v[210:213], v[6:9]
	s_waitcnt lgkmcnt(8)
	v_mfma_f32_16x16x32_bf16 v[42:45], v[226:229], v[198:201], v[42:45]
	v_mfma_f32_16x16x32_bf16 v[46:49], v[226:229], v[202:205], v[46:49]
	v_mfma_f32_16x16x32_bf16 v[10:13], v[226:229], v[206:209], v[10:13]
	v_mfma_f32_16x16x32_bf16 v[14:17], v[226:229], v[210:213], v[14:17]
	s_add_i32 s24, s24, 2
	s_add_u32 s98, s98, 256
	s_addc_u32 s99, s99, 0
	s_add_u32 s100, s100, 256
	s_addc_u32 s101, s101, 0
	s_waitcnt lgkmcnt(0)
	s_barrier
	s_cmp_lt_u32 s24, 30
	s_cbranch_scc1 .LBB0_387
	ds_read_b128 v[170:173], v150 offset:36880
	ds_read_b128 v[154:157], v149 offset:16
	ds_read_b128 v[158:161], v149 offset:2320
	ds_read_b128 v[174:177], v150 offset:39184
	ds_read_b128 v[162:165], v149 offset:4624
	ds_read_b128 v[166:169], v149 offset:6928
	ds_read_b128 v[178:181], v150 offset:41488
	ds_read_b128 v[182:185], v150 offset:43792
	s_waitcnt lgkmcnt(6)
	v_mfma_f32_16x16x32_bf16 v[50:53], v[170:173], v[154:157], v[50:53]
	s_waitcnt lgkmcnt(5)
	v_mfma_f32_16x16x32_bf16 v[54:57], v[170:173], v[158:161], v[54:57]
	s_waitcnt lgkmcnt(4)
	v_mfma_f32_16x16x32_bf16 v[58:61], v[174:177], v[154:157], v[58:61]
	v_mfma_f32_16x16x32_bf16 v[62:65], v[174:177], v[158:161], v[62:65]
	ds_read_b128 v[214:217], v150 offset:36944
	ds_read_b128 v[198:201], v149 offset:80
	ds_read_b128 v[202:205], v149 offset:2384
	ds_read_b128 v[218:221], v150 offset:39248
	s_waitcnt lgkmcnt(7)
	v_mfma_f32_16x16x32_bf16 v[18:21], v[170:173], v[162:165], v[18:21]
	v_mfma_f32_16x16x32_bf16 v[26:29], v[174:177], v[162:165], v[26:29]
	s_waitcnt lgkmcnt(6)
	v_mfma_f32_16x16x32_bf16 v[22:25], v[170:173], v[166:169], v[22:25]
	v_mfma_f32_16x16x32_bf16 v[30:33], v[174:177], v[166:169], v[30:33]
	ds_read_b128 v[206:209], v149 offset:4688
	ds_read_b128 v[210:213], v149 offset:6992
	ds_read_b128 v[222:225], v150 offset:41552
	ds_read_b128 v[226:229], v150 offset:43856
	s_waitcnt lgkmcnt(9)
	v_mfma_f32_16x16x32_bf16 v[34:37], v[178:181], v[154:157], v[34:37]
	v_mfma_f32_16x16x32_bf16 v[38:41], v[178:181], v[158:161], v[38:41]
	s_waitcnt vmcnt(6)
	ds_write_b128 v146, v[98:101] offset:18448
	ds_write_b128 v146, v[102:105] offset:55312
	v_mfma_f32_16x16x32_bf16 v[2:5], v[178:181], v[162:165], v[2:5]
	v_mfma_f32_16x16x32_bf16 v[6:9], v[178:181], v[166:169], v[6:9]
	s_waitcnt lgkmcnt(10)
	v_mfma_f32_16x16x32_bf16 v[42:45], v[182:185], v[154:157], v[42:45]
	v_mfma_f32_16x16x32_bf16 v[46:49], v[182:185], v[158:161], v[46:49]
	s_waitcnt vmcnt(4)
	ds_write_b128 v146, v[106:109] offset:23056
	ds_write_b128 v146, v[110:113] offset:59920
	v_mfma_f32_16x16x32_bf16 v[10:13], v[182:185], v[162:165], v[10:13]
	v_mfma_f32_16x16x32_bf16 v[14:17], v[182:185], v[166:169], v[14:17]
	s_waitcnt lgkmcnt(10)
	v_mfma_f32_16x16x32_bf16 v[50:53], v[214:217], v[198:201], v[50:53]
	s_waitcnt lgkmcnt(9)
	v_mfma_f32_16x16x32_bf16 v[54:57], v[214:217], v[202:205], v[54:57]
	s_waitcnt vmcnt(2)
	ds_write_b128 v146, v[114:117] offset:27664
	ds_write_b128 v146, v[118:121] offset:64528
	s_waitcnt lgkmcnt(10)
	v_mfma_f32_16x16x32_bf16 v[58:61], v[218:221], v[198:201], v[58:61]
	v_mfma_f32_16x16x32_bf16 v[62:65], v[218:221], v[202:205], v[62:65]
	s_waitcnt lgkmcnt(9)
	v_mfma_f32_16x16x32_bf16 v[18:21], v[214:217], v[206:209], v[18:21]
	v_mfma_f32_16x16x32_bf16 v[26:29], v[218:221], v[206:209], v[26:29]
	s_waitcnt vmcnt(0)
	ds_write_b128 v146, v[122:125] offset:32272
	ds_write_b128 v147, v[126:129] offset:32256
	s_waitcnt lgkmcnt(10)
	v_mfma_f32_16x16x32_bf16 v[22:25], v[214:217], v[210:213], v[22:25]
	v_mfma_f32_16x16x32_bf16 v[30:33], v[218:221], v[210:213], v[30:33]
	s_waitcnt lgkmcnt(9)
	v_mfma_f32_16x16x32_bf16 v[34:37], v[222:225], v[198:201], v[34:37]
	v_mfma_f32_16x16x32_bf16 v[38:41], v[222:225], v[202:205], v[38:41]
	v_mfma_f32_16x16x32_bf16 v[2:5], v[222:225], v[206:209], v[2:5]
	v_mfma_f32_16x16x32_bf16 v[6:9], v[222:225], v[210:213], v[6:9]
	s_waitcnt lgkmcnt(8)
	v_mfma_f32_16x16x32_bf16 v[42:45], v[226:229], v[198:201], v[42:45]
	v_mfma_f32_16x16x32_bf16 v[46:49], v[226:229], v[202:205], v[46:49]
	v_mfma_f32_16x16x32_bf16 v[10:13], v[226:229], v[206:209], v[10:13]
	v_mfma_f32_16x16x32_bf16 v[14:17], v[226:229], v[210:213], v[14:17]
	s_waitcnt lgkmcnt(0)
	s_barrier
; template <bool SWAP, class Epi>
; DI void gemm_tile(const u16* __restrict__ A, int lda, const u16* __restrict__ Bt, int ldb, int K, int m0, int n0, char* smem, Epi&& epi) {
;     ...
;   auto compute = [&](int buf) __attribute__((always_inline)) {
;     bf16x8 af[2][2], bfr[2][2];
;     af[0][0] = *(const bf16x8*)(Asb + buf * 128 * 72);
;     af[0][1] = *(const bf16x8*)(Asb + buf * 128 * 72 + 32 * 72);
;     bfr[0][0] = *(const bf16x8*)(Bsb + buf * 128 * 72);
;     bfr[0][1] = *(const bf16x8*)(Bsb + buf * 128 * 72 + 32 * 72);
; #pragma unroll
;     for (int ks = 0; ks < 4; ++ks) {
;       const int c = ks & 1, n = c ^ 1;
;       if (ks < 3) {
;         af[n][0] = *(const bf16x8*)(Asb + buf * 128 * 72 + (ks + 1) * 16);
;         af[n][1] = *(const bf16x8*)(Asb + buf * 128 * 72 + 32 * 72 + (ks + 1) * 16);
;         bfr[n][0] = *(const bf16x8*)(Bsb + buf * 128 * 72 + (ks + 1) * 16);
;         bfr[n][1] = *(const bf16x8*)(Bsb + buf * 128 * 72 + 32 * 72 + (ks + 1) * 16);
;       }
;       __builtin_amdgcn_sched_barrier(0);
; #pragma unroll
;       for (int mi = 0; mi < 2; ++mi)
; #pragma unroll
;         for (int ni = 0; ni < 2; ++ni) {
;           if (SWAP) acc[mi][ni] = MFMA(bfr[c][ni], af[c][mi], acc[mi][ni]);
;           else acc[mi][ni] = MFMA(af[c][mi], bfr[c][ni], acc[mi][ni]);
;         }
;       __builtin_amdgcn_sched_barrier(0);
;     }
;   };
;   for (int kt = 0; kt < KT; kt += 2) {
;     if (kt + 2 < KT) {
;       const int k0 = (kt + 2) << 6;
; #pragma unroll
;       for (int i = 0; i < 4; ++i) { ra0[i] = *(const u32x4*)(ag + (size_t)i * 32 * lda + k0); rb0[i] = *(const u32x4*)(bg + (size_t)i * 32 * ldb + k0); }
;     }
;     compute(0);
; #pragma unroll
;     for (int i = 0; i < 4; ++i) { *(u32x4*)(asw + 128 * 72 + 32 * i * 72) = ra1[i]; *(u32x4*)(bsw + 128 * 72 + 32 * i * 72) = rb1[i]; }
;     __syncthreads();
;     if (kt + 3 < KT) {
;       const int k0 = (kt + 3) << 6;
; #pragma unroll
;       for (int i = 0; i < 4; ++i) { ra1[i] = *(const u32x4*)(ag + (size_t)i * 32 * lda + k0); rb1[i] = *(const u32x4*)(bg + (size_t)i * 32 * ldb + k0); }
;     }
;     compute(1);
;     if (kt + 2 < KT) {
; #pragma unroll
;       for (int i = 0; i < 4; ++i) { *(u32x4*)(asw + 32 * i * 72) = ra0[i]; *(u32x4*)(bsw + 32 * i * 72) = rb0[i]; }
;     }
;     __syncthreads();
;   }
;   epi(acc, m0 + wm * 64, n0 + wn * 64, r, hi);
	ds_read_b128 v[170:173], v150 offset:55312
	ds_read_b128 v[154:157], v149 offset:18448
	ds_read_b128 v[158:161], v149 offset:20752
	ds_read_b128 v[174:177], v150 offset:57616
	ds_read_b128 v[162:165], v149 offset:23056
	ds_read_b128 v[166:169], v149 offset:25360
	ds_read_b128 v[178:181], v150 offset:59920
	ds_read_b128 v[182:185], v150 offset:62224
	s_waitcnt lgkmcnt(6)
	v_mfma_f32_16x16x32_bf16 v[50:53], v[170:173], v[154:157], v[50:53]
	s_waitcnt lgkmcnt(5)
	v_mfma_f32_16x16x32_bf16 v[54:57], v[170:173], v[158:161], v[54:57]
	s_waitcnt lgkmcnt(4)
	v_mfma_f32_16x16x32_bf16 v[58:61], v[174:177], v[154:157], v[58:61]
	v_mfma_f32_16x16x32_bf16 v[62:65], v[174:177], v[158:161], v[62:65]
	ds_read_b128 v[214:217], v150 offset:55376
	ds_read_b128 v[198:201], v149 offset:18512
	ds_read_b128 v[202:205], v149 offset:20816
	ds_read_b128 v[218:221], v150 offset:57680
	s_waitcnt lgkmcnt(7)
	v_mfma_f32_16x16x32_bf16 v[18:21], v[170:173], v[162:165], v[18:21]
	v_mfma_f32_16x16x32_bf16 v[26:29], v[174:177], v[162:165], v[26:29]
	s_waitcnt lgkmcnt(6)
	v_mfma_f32_16x16x32_bf16 v[22:25], v[170:173], v[166:169], v[22:25]
	v_mfma_f32_16x16x32_bf16 v[30:33], v[174:177], v[166:169], v[30:33]
	ds_read_b128 v[206:209], v149 offset:23120
	ds_read_b128 v[210:213], v149 offset:25424
	ds_read_b128 v[222:225], v150 offset:59984
	ds_read_b128 v[226:229], v150 offset:62288
	s_waitcnt lgkmcnt(9)
	v_mfma_f32_16x16x32_bf16 v[34:37], v[178:181], v[154:157], v[34:37]
	v_mfma_f32_16x16x32_bf16 v[38:41], v[178:181], v[158:161], v[38:41]
	v_mfma_f32_16x16x32_bf16 v[2:5], v[178:181], v[162:165], v[2:5]
	v_mfma_f32_16x16x32_bf16 v[6:9], v[178:181], v[166:169], v[6:9]
	s_waitcnt lgkmcnt(8)
	v_mfma_f32_16x16x32_bf16 v[42:45], v[182:185], v[154:157], v[42:45]
	v_mfma_f32_16x16x32_bf16 v[46:49], v[182:185], v[158:161], v[46:49]
	v_mfma_f32_16x16x32_bf16 v[10:13], v[182:185], v[162:165], v[10:13]
	v_mfma_f32_16x16x32_bf16 v[14:17], v[182:185], v[166:169], v[14:17]
	s_waitcnt lgkmcnt(6)
	v_mfma_f32_16x16x32_bf16 v[50:53], v[214:217], v[198:201], v[50:53]
	s_waitcnt lgkmcnt(5)
	v_mfma_f32_16x16x32_bf16 v[54:57], v[214:217], v[202:205], v[54:57]
	s_waitcnt lgkmcnt(4)
	v_mfma_f32_16x16x32_bf16 v[58:61], v[218:221], v[198:201], v[58:61]
	v_mfma_f32_16x16x32_bf16 v[62:65], v[218:221], v[202:205], v[62:65]
	s_waitcnt lgkmcnt(3)
	v_mfma_f32_16x16x32_bf16 v[18:21], v[214:217], v[206:209], v[18:21]
	v_mfma_f32_16x16x32_bf16 v[26:29], v[218:221], v[206:209], v[26:29]
	s_waitcnt lgkmcnt(2)
	v_mfma_f32_16x16x32_bf16 v[22:25], v[214:217], v[210:213], v[22:25]
	v_mfma_f32_16x16x32_bf16 v[30:33], v[218:221], v[210:213], v[30:33]
	s_waitcnt lgkmcnt(1)
	v_mfma_f32_16x16x32_bf16 v[34:37], v[222:225], v[198:201], v[34:37]
	v_mfma_f32_16x16x32_bf16 v[38:41], v[222:225], v[202:205], v[38:41]
	v_mfma_f32_16x16x32_bf16 v[2:5], v[222:225], v[206:209], v[2:5]
	v_mfma_f32_16x16x32_bf16 v[6:9], v[222:225], v[210:213], v[6:9]
	s_waitcnt lgkmcnt(0)
	v_mfma_f32_16x16x32_bf16 v[42:45], v[226:229], v[198:201], v[42:45]
	v_mfma_f32_16x16x32_bf16 v[46:49], v[226:229], v[202:205], v[46:49]
	v_mfma_f32_16x16x32_bf16 v[10:13], v[226:229], v[206:209], v[10:13]
	v_mfma_f32_16x16x32_bf16 v[14:17], v[226:229], v[210:213], v[14:17]
	s_nop 7
	s_nop 7
	v_permlane16_swap_b32_e32 v50, v54
	v_permlane16_swap_b32_e32 v51, v55
	v_permlane16_swap_b32_e32 v52, v56
	v_permlane16_swap_b32_e32 v53, v57
	v_permlane16_swap_b32_e32 v58, v62
	v_permlane16_swap_b32_e32 v59, v63
	v_permlane16_swap_b32_e32 v60, v64
	v_permlane16_swap_b32_e32 v61, v65
	v_permlane16_swap_b32_e32 v34, v38
	v_permlane16_swap_b32_e32 v35, v39
	v_permlane16_swap_b32_e32 v36, v40
	v_permlane16_swap_b32_e32 v37, v41
	v_permlane16_swap_b32_e32 v42, v46
	v_permlane16_swap_b32_e32 v43, v47
	v_permlane16_swap_b32_e32 v44, v48
	v_permlane16_swap_b32_e32 v45, v49
	v_permlane16_swap_b32_e32 v18, v22
	v_permlane16_swap_b32_e32 v19, v23
	v_permlane16_swap_b32_e32 v20, v24
	v_permlane16_swap_b32_e32 v21, v25
	v_permlane16_swap_b32_e32 v26, v30
	v_permlane16_swap_b32_e32 v27, v31
	v_permlane16_swap_b32_e32 v28, v32
	v_permlane16_swap_b32_e32 v29, v33
	v_permlane16_swap_b32_e32 v2, v6
	v_permlane16_swap_b32_e32 v3, v7
	v_permlane16_swap_b32_e32 v4, v8
	v_permlane16_swap_b32_e32 v5, v9
	v_permlane16_swap_b32_e32 v10, v14
	v_permlane16_swap_b32_e32 v11, v15
	v_permlane16_swap_b32_e32 v12, v16
	v_permlane16_swap_b32_e32 v13, v17
	v_permlane32_swap_b32_e32 v50, v54
	v_permlane32_swap_b32_e32 v51, v55
	v_permlane32_swap_b32_e32 v52, v56
	v_permlane32_swap_b32_e32 v53, v57
	v_permlane32_swap_b32_e32 v58, v62
	v_permlane32_swap_b32_e32 v59, v63
	v_permlane32_swap_b32_e32 v60, v64
	v_permlane32_swap_b32_e32 v61, v65
	v_permlane32_swap_b32_e32 v34, v38
	v_permlane32_swap_b32_e32 v35, v39
	v_permlane32_swap_b32_e32 v36, v40
	v_permlane32_swap_b32_e32 v37, v41
	v_permlane32_swap_b32_e32 v42, v46
	v_permlane32_swap_b32_e32 v43, v47
	v_permlane32_swap_b32_e32 v44, v48
	v_permlane32_swap_b32_e32 v45, v49
	v_permlane32_swap_b32_e32 v18, v22
	v_permlane32_swap_b32_e32 v19, v23
	v_permlane32_swap_b32_e32 v20, v24
	v_permlane32_swap_b32_e32 v21, v25
	v_permlane32_swap_b32_e32 v26, v30
	v_permlane32_swap_b32_e32 v27, v31
	v_permlane32_swap_b32_e32 v28, v32
	v_permlane32_swap_b32_e32 v29, v33
	v_permlane32_swap_b32_e32 v2, v6
	v_permlane32_swap_b32_e32 v3, v7
	v_permlane32_swap_b32_e32 v4, v8
	v_permlane32_swap_b32_e32 v5, v9
	v_permlane32_swap_b32_e32 v10, v14
	v_permlane32_swap_b32_e32 v11, v15
	v_permlane32_swap_b32_e32 v12, v16
	v_permlane32_swap_b32_e32 v13, v17
	s_waitcnt lgkmcnt(0)
	s_barrier
	s_branch .LBB0_393

; #define MFMA(a, b, c) __builtin_amdgcn_mfma_f32_32x32x16_bf16((a), (b), (c), 0, 0, 0)
; template <bool SWAP, class Epi>
; DI void gemm_tile(const u16* __restrict__ A, int lda, const u16* __restrict__ Bt, int ldb, int K, int m0, int n0, char* smem, Epi&& epi) {
;     ...
;   auto compute = [&](int buf) __attribute__((always_inline)) {
;     bf16x8 af[2][2], bfr[2][2];
;     af[0][0] = *(const bf16x8*)(Asb + buf * 128 * 72);
;     af[0][1] = *(const bf16x8*)(Asb + buf * 128 * 72 + 32 * 72);
;     bfr[0][0] = *(const bf16x8*)(Bsb + buf * 128 * 72);
;     bfr[0][1] = *(const bf16x8*)(Bsb + buf * 128 * 72 + 32 * 72);
; #pragma unroll
;     for (int ks = 0; ks < 4; ++ks) {
;       const int c = ks & 1, n = c ^ 1;
;       if (ks < 3) {
;         af[n][0] = *(const bf16x8*)(Asb + buf * 128 * 72 + (ks + 1) * 16);
;         af[n][1] = *(const bf16x8*)(Asb + buf * 128 * 72 + 32 * 72 + (ks + 1) * 16);
;         bfr[n][0] = *(const bf16x8*)(Bsb + buf * 128 * 72 + (ks + 1) * 16);
;         bfr[n][1] = *(const bf16x8*)(Bsb + buf * 128 * 72 + 32 * 72 + (ks + 1) * 16);
;       }
;       __builtin_amdgcn_sched_barrier(0);
; #pragma unroll
;       for (int mi = 0; mi < 2; ++mi)
; #pragma unroll
;         for (int ni = 0; ni < 2; ++ni) {
;           if (SWAP) acc[mi][ni] = MFMA(bfr[c][ni], af[c][mi], acc[mi][ni]);
;           else acc[mi][ni] = MFMA(af[c][mi], bfr[c][ni], acc[mi][ni]);
;         }
;       __builtin_amdgcn_sched_barrier(0);
;     }
;   };
;   for (int kt = 0; kt < KT; kt += 2) {
;     if (kt + 2 < KT) {
;       const int k0 = (kt + 2) << 6;
; #pragma unroll
;       for (int i = 0; i < 4; ++i) { ra0[i] = *(const u32x4*)(ag + (size_t)i * 32 * lda + k0); rb0[i] = *(const u32x4*)(bg + (size_t)i * 32 * ldb + k0); }
;     }
;     compute(0);
; #pragma unroll
;     for (int i = 0; i < 4; ++i) { *(u32x4*)(asw + 128 * 72 + 32 * i * 72) = ra1[i]; *(u32x4*)(bsw + 128 * 72 + 32 * i * 72) = rb1[i]; }
;     __syncthreads();
;     if (kt + 3 < KT) {
;       const int k0 = (kt + 3) << 6;
; #pragma unroll
;       for (int i = 0; i < 4; ++i) { ra1[i] = *(const u32x4*)(ag + (size_t)i * 32 * lda + k0); rb1[i] = *(const u32x4*)(bg + (size_t)i * 32 * ldb + k0); }
;     }
;     compute(1);
;     if (kt + 2 < KT) {
; #pragma unroll
;       for (int i = 0; i < 4; ++i) { *(u32x4*)(asw + 32 * i * 72) = ra0[i]; *(u32x4*)(bsw + 32 * i * 72) = rb0[i]; }
;     }
;     __syncthreads();
;   }
.LBB0_748:
	global_load_dwordx4 v[66:69], v194, s[100:101] offset:256
	global_load_dwordx4 v[70:73], v190, s[98:99] offset:256
	global_load_dwordx4 v[74:77], v195, s[100:101] offset:256
	global_load_dwordx4 v[78:81], v191, s[98:99] offset:256
	global_load_dwordx4 v[82:85], v196, s[100:101] offset:256
	global_load_dwordx4 v[86:89], v192, s[98:99] offset:256
	global_load_dwordx4 v[90:93], v197, s[100:101] offset:256
	global_load_dwordx4 v[94:97], v193, s[98:99] offset:256
	ds_read_b128 v[166:169], v148 offset:36880
	ds_read_b128 v[150:153], v147 offset:16
	ds_read_b128 v[154:157], v147 offset:2320
	ds_read_b128 v[170:173], v148 offset:39184
	ds_read_b128 v[158:161], v147 offset:4624
	ds_read_b128 v[162:165], v147 offset:6928
	ds_read_b128 v[174:177], v148 offset:41488
	ds_read_b128 v[178:181], v148 offset:43792
	s_waitcnt lgkmcnt(6)
	v_mfma_f32_16x16x32_bf16 v[50:53], v[166:169], v[150:153], v[50:53]
	s_waitcnt lgkmcnt(5)
	v_mfma_f32_16x16x32_bf16 v[54:57], v[166:169], v[154:157], v[54:57]
	s_waitcnt lgkmcnt(4)
	v_mfma_f32_16x16x32_bf16 v[58:61], v[170:173], v[150:153], v[58:61]
	v_mfma_f32_16x16x32_bf16 v[62:65], v[170:173], v[154:157], v[62:65]
	ds_read_b128 v[214:217], v148 offset:36944
	ds_read_b128 v[198:201], v147 offset:80
	ds_read_b128 v[202:205], v147 offset:2384
	ds_read_b128 v[218:221], v148 offset:39248
	s_waitcnt lgkmcnt(7)
	v_mfma_f32_16x16x32_bf16 v[18:21], v[166:169], v[158:161], v[18:21]
	v_mfma_f32_16x16x32_bf16 v[26:29], v[170:173], v[158:161], v[26:29]
	s_waitcnt lgkmcnt(6)
	v_mfma_f32_16x16x32_bf16 v[22:25], v[166:169], v[162:165], v[22:25]
	v_mfma_f32_16x16x32_bf16 v[30:33], v[170:173], v[162:165], v[30:33]
	ds_read_b128 v[206:209], v147 offset:4688
	ds_read_b128 v[210:213], v147 offset:6992
	ds_read_b128 v[222:225], v148 offset:41552
	ds_read_b128 v[226:229], v148 offset:43856
	s_waitcnt lgkmcnt(9)
	v_mfma_f32_16x16x32_bf16 v[34:37], v[174:177], v[150:153], v[34:37]
	v_mfma_f32_16x16x32_bf16 v[38:41], v[174:177], v[154:157], v[38:41]
	s_waitcnt vmcnt(14)
	ds_write_b128 v144, v[98:101] offset:18448
	ds_write_b128 v144, v[102:105] offset:55312
	v_mfma_f32_16x16x32_bf16 v[2:5], v[174:177], v[158:161], v[2:5]
	v_mfma_f32_16x16x32_bf16 v[6:9], v[174:177], v[162:165], v[6:9]
	s_waitcnt lgkmcnt(10)
	v_mfma_f32_16x16x32_bf16 v[42:45], v[178:181], v[150:153], v[42:45]
	v_mfma_f32_16x16x32_bf16 v[46:49], v[178:181], v[154:157], v[46:49]
	s_waitcnt vmcnt(12)
	ds_write_b128 v144, v[106:109] offset:23056
	ds_write_b128 v144, v[110:113] offset:59920
	v_mfma_f32_16x16x32_bf16 v[10:13], v[178:181], v[158:161], v[10:13]
	v_mfma_f32_16x16x32_bf16 v[14:17], v[178:181], v[162:165], v[14:17]
	s_waitcnt lgkmcnt(10)
	v_mfma_f32_16x16x32_bf16 v[50:53], v[214:217], v[198:201], v[50:53]
	s_waitcnt lgkmcnt(9)
	v_mfma_f32_16x16x32_bf16 v[54:57], v[214:217], v[202:205], v[54:57]
	s_waitcnt vmcnt(10)
	ds_write_b128 v144, v[114:117] offset:27664
	ds_write_b128 v144, v[118:121] offset:64528
	s_waitcnt lgkmcnt(10)
	v_mfma_f32_16x16x32_bf16 v[58:61], v[218:221], v[198:201], v[58:61]
	v_mfma_f32_16x16x32_bf16 v[62:65], v[218:221], v[202:205], v[62:65]
	s_waitcnt lgkmcnt(9)
	v_mfma_f32_16x16x32_bf16 v[18:21], v[214:217], v[206:209], v[18:21]
	v_mfma_f32_16x16x32_bf16 v[26:29], v[218:221], v[206:209], v[26:29]
	s_waitcnt vmcnt(8)
	ds_write_b128 v144, v[122:125] offset:32272
	ds_write_b128 v145, v[126:129] offset:32256
	s_waitcnt lgkmcnt(10)
	v_mfma_f32_16x16x32_bf16 v[22:25], v[214:217], v[210:213], v[22:25]
	v_mfma_f32_16x16x32_bf16 v[30:33], v[218:221], v[210:213], v[30:33]
	s_waitcnt lgkmcnt(9)
	v_mfma_f32_16x16x32_bf16 v[34:37], v[222:225], v[198:201], v[34:37]
	v_mfma_f32_16x16x32_bf16 v[38:41], v[222:225], v[202:205], v[38:41]
	v_mfma_f32_16x16x32_bf16 v[2:5], v[222:225], v[206:209], v[2:5]
	v_mfma_f32_16x16x32_bf16 v[6:9], v[222:225], v[210:213], v[6:9]
	s_waitcnt lgkmcnt(8)
	v_mfma_f32_16x16x32_bf16 v[42:45], v[226:229], v[198:201], v[42:45]
	v_mfma_f32_16x16x32_bf16 v[46:49], v[226:229], v[202:205], v[46:49]
	v_mfma_f32_16x16x32_bf16 v[10:13], v[226:229], v[206:209], v[10:13]
	v_mfma_f32_16x16x32_bf16 v[14:17], v[226:229], v[210:213], v[14:17]
	s_waitcnt lgkmcnt(0)
	s_barrier
	global_load_dwordx4 v[98:101], v194, s[100:101] offset:384
	global_load_dwordx4 v[102:105], v190, s[98:99] offset:384
	global_load_dwordx4 v[106:109], v195, s[100:101] offset:384
	global_load_dwordx4 v[110:113], v191, s[98:99] offset:384
	global_load_dwordx4 v[114:117], v196, s[100:101] offset:384
	global_load_dwordx4 v[118:121], v192, s[98:99] offset:384
	global_load_dwordx4 v[122:125], v197, s[100:101] offset:384
	global_load_dwordx4 v[126:129], v193, s[98:99] offset:384
	ds_read_b128 v[166:169], v148 offset:55312
	ds_read_b128 v[150:153], v147 offset:18448
	ds_read_b128 v[154:157], v147 offset:20752
	ds_read_b128 v[170:173], v148 offset:57616
	ds_read_b128 v[158:161], v147 offset:23056
	ds_read_b128 v[162:165], v147 offset:25360
	ds_read_b128 v[174:177], v148 offset:59920
	ds_read_b128 v[178:181], v148 offset:62224
	s_waitcnt lgkmcnt(6)
	v_mfma_f32_16x16x32_bf16 v[50:53], v[166:169], v[150:153], v[50:53]
	s_waitcnt lgkmcnt(5)
	v_mfma_f32_16x16x32_bf16 v[54:57], v[166:169], v[154:157], v[54:57]
	s_waitcnt lgkmcnt(4)
	v_mfma_f32_16x16x32_bf16 v[58:61], v[170:173], v[150:153], v[58:61]
	v_mfma_f32_16x16x32_bf16 v[62:65], v[170:173], v[154:157], v[62:65]
	ds_read_b128 v[214:217], v148 offset:55376
	ds_read_b128 v[198:201], v147 offset:18512
	ds_read_b128 v[202:205], v147 offset:20816
	ds_read_b128 v[218:221], v148 offset:57680
	s_waitcnt lgkmcnt(7)
	v_mfma_f32_16x16x32_bf16 v[18:21], v[166:169], v[158:161], v[18:21]
	v_mfma_f32_16x16x32_bf16 v[26:29], v[170:173], v[158:161], v[26:29]
	s_waitcnt lgkmcnt(6)
; #define MFMA(a, b, c) __builtin_amdgcn_mfma_f32_32x32x16_bf16((a), (b), (c), 0, 0, 0)
; template <bool SWAP, class Epi>
; DI void gemm_tile(const u16* __restrict__ A, int lda, const u16* __restrict__ Bt, int ldb, int K, int m0, int n0, char* smem, Epi&& epi) {
;     ...
;   auto compute = [&](int buf) __attribute__((always_inline)) {
;     bf16x8 af[2][2], bfr[2][2];
;     af[0][0] = *(const bf16x8*)(Asb + buf * 128 * 72);
;     af[0][1] = *(const bf16x8*)(Asb + buf * 128 * 72 + 32 * 72);
;     bfr[0][0] = *(const bf16x8*)(Bsb + buf * 128 * 72);
;     bfr[0][1] = *(const bf16x8*)(Bsb + buf * 128 * 72 + 32 * 72);
; #pragma unroll
;     for (int ks = 0; ks < 4; ++ks) {
;       const int c = ks & 1, n = c ^ 1;
;       if (ks < 3) {
;         af[n][0] = *(const bf16x8*)(Asb + buf * 128 * 72 + (ks + 1) * 16);
;         af[n][1] = *(const bf16x8*)(Asb + buf * 128 * 72 + 32 * 72 + (ks + 1) * 16);
;         bfr[n][0] = *(const bf16x8*)(Bsb + buf * 128 * 72 + (ks + 1) * 16);
;         bfr[n][1] = *(const bf16x8*)(Bsb + buf * 128 * 72 + 32 * 72 + (ks + 1) * 16);
;       }
;       __builtin_amdgcn_sched_barrier(0);
; #pragma unroll
;       for (int mi = 0; mi < 2; ++mi)
; #pragma unroll
;         for (int ni = 0; ni < 2; ++ni) {
;           if (SWAP) acc[mi][ni] = MFMA(bfr[c][ni], af[c][mi], acc[mi][ni]);
;           else acc[mi][ni] = MFMA(af[c][mi], bfr[c][ni], acc[mi][ni]);
;         }
;       __builtin_amdgcn_sched_barrier(0);
;     }
;   };
;   for (int kt = 0; kt < KT; kt += 2) {
;     if (kt + 2 < KT) {
;       const int k0 = (kt + 2) << 6;
; #pragma unroll
;       for (int i = 0; i < 4; ++i) { ra0[i] = *(const u32x4*)(ag + (size_t)i * 32 * lda + k0); rb0[i] = *(const u32x4*)(bg + (size_t)i * 32 * ldb + k0); }
;     }
;     compute(0);
; #pragma unroll
;     for (int i = 0; i < 4; ++i) { *(u32x4*)(asw + 128 * 72 + 32 * i * 72) = ra1[i]; *(u32x4*)(bsw + 128 * 72 + 32 * i * 72) = rb1[i]; }
;     __syncthreads();
;     if (kt + 3 < KT) {
;       const int k0 = (kt + 3) << 6;
; #pragma unroll
;       for (int i = 0; i < 4; ++i) { ra1[i] = *(const u32x4*)(ag + (size_t)i * 32 * lda + k0); rb1[i] = *(const u32x4*)(bg + (size_t)i * 32 * ldb + k0); }
;     }
;     compute(1);
;     if (kt + 2 < KT) {
; #pragma unroll
;       for (int i = 0; i < 4; ++i) { *(u32x4*)(asw + 32 * i * 72) = ra0[i]; *(u32x4*)(bsw + 32 * i * 72) = rb0[i]; }
;     }
;     __syncthreads();
;   }
	v_mfma_f32_16x16x32_bf16 v[22:25], v[166:169], v[162:165], v[22:25]
	v_mfma_f32_16x16x32_bf16 v[30:33], v[170:173], v[162:165], v[30:33]
	ds_read_b128 v[206:209], v147 offset:23120
	ds_read_b128 v[210:213], v147 offset:25424
	ds_read_b128 v[222:225], v148 offset:59984
	ds_read_b128 v[226:229], v148 offset:62288
	s_waitcnt lgkmcnt(9)
	v_mfma_f32_16x16x32_bf16 v[34:37], v[174:177], v[150:153], v[34:37]
	v_mfma_f32_16x16x32_bf16 v[38:41], v[174:177], v[154:157], v[38:41]
	s_waitcnt vmcnt(14)
	ds_write_b128 v144, v[66:69] offset:16
	ds_write_b128 v144, v[70:73] offset:36880
	v_mfma_f32_16x16x32_bf16 v[2:5], v[174:177], v[158:161], v[2:5]
	v_mfma_f32_16x16x32_bf16 v[6:9], v[174:177], v[162:165], v[6:9]
	s_waitcnt lgkmcnt(10)
	v_mfma_f32_16x16x32_bf16 v[42:45], v[178:181], v[150:153], v[42:45]
	v_mfma_f32_16x16x32_bf16 v[46:49], v[178:181], v[154:157], v[46:49]
	s_waitcnt vmcnt(12)
	ds_write_b128 v144, v[74:77] offset:4624
	ds_write_b128 v144, v[78:81] offset:41488
	v_mfma_f32_16x16x32_bf16 v[10:13], v[178:181], v[158:161], v[10:13]
	v_mfma_f32_16x16x32_bf16 v[14:17], v[178:181], v[162:165], v[14:17]
	s_waitcnt lgkmcnt(10)
	v_mfma_f32_16x16x32_bf16 v[50:53], v[214:217], v[198:201], v[50:53]
	s_waitcnt lgkmcnt(9)
	v_mfma_f32_16x16x32_bf16 v[54:57], v[214:217], v[202:205], v[54:57]
	s_waitcnt vmcnt(10)
	ds_write_b128 v144, v[82:85] offset:9232
	ds_write_b128 v144, v[86:89] offset:46096
	s_waitcnt lgkmcnt(10)
	v_mfma_f32_16x16x32_bf16 v[58:61], v[218:221], v[198:201], v[58:61]
	v_mfma_f32_16x16x32_bf16 v[62:65], v[218:221], v[202:205], v[62:65]
	s_waitcnt lgkmcnt(9)
	v_mfma_f32_16x16x32_bf16 v[18:21], v[214:217], v[206:209], v[18:21]
	v_mfma_f32_16x16x32_bf16 v[26:29], v[218:221], v[206:209], v[26:29]
	s_waitcnt vmcnt(8)
	ds_write_b128 v144, v[90:93] offset:13840
	ds_write_b128 v144, v[94:97] offset:50704
	s_waitcnt lgkmcnt(10)
	v_mfma_f32_16x16x32_bf16 v[22:25], v[214:217], v[210:213], v[22:25]
	v_mfma_f32_16x16x32_bf16 v[30:33], v[218:221], v[210:213], v[30:33]
	s_waitcnt lgkmcnt(9)
	v_mfma_f32_16x16x32_bf16 v[34:37], v[222:225], v[198:201], v[34:37]
	v_mfma_f32_16x16x32_bf16 v[38:41], v[222:225], v[202:205], v[38:41]
	v_mfma_f32_16x16x32_bf16 v[2:5], v[222:225], v[206:209], v[2:5]
	v_mfma_f32_16x16x32_bf16 v[6:9], v[222:225], v[210:213], v[6:9]
	s_waitcnt lgkmcnt(8)
	v_mfma_f32_16x16x32_bf16 v[42:45], v[226:229], v[198:201], v[42:45]
	v_mfma_f32_16x16x32_bf16 v[46:49], v[226:229], v[202:205], v[46:49]
	v_mfma_f32_16x16x32_bf16 v[10:13], v[226:229], v[206:209], v[10:13]
	v_mfma_f32_16x16x32_bf16 v[14:17], v[226:229], v[210:213], v[14:17]
	s_add_i32 s20, s20, 2
	s_add_u32 s98, s98, 256
	s_addc_u32 s99, s99, 0
	s_add_u32 s100, s100, 256
	s_addc_u32 s101, s101, 0
	s_waitcnt lgkmcnt(0)
	s_barrier
	s_cmp_lt_u32 s20, 30
	s_cbranch_scc1 .LBB0_748
	ds_read_b128 v[166:169], v148 offset:36880
	ds_read_b128 v[150:153], v147 offset:16
	ds_read_b128 v[154:157], v147 offset:2320
	ds_read_b128 v[170:173], v148 offset:39184
	ds_read_b128 v[158:161], v147 offset:4624
	ds_read_b128 v[162:165], v147 offset:6928
	ds_read_b128 v[174:177], v148 offset:41488
	ds_read_b128 v[178:181], v148 offset:43792
	s_waitcnt lgkmcnt(6)
	v_mfma_f32_16x16x32_bf16 v[50:53], v[166:169], v[150:153], v[50:53]
	s_waitcnt lgkmcnt(5)
	v_mfma_f32_16x16x32_bf16 v[54:57], v[166:169], v[154:157], v[54:57]
	s_waitcnt lgkmcnt(4)
	v_mfma_f32_16x16x32_bf16 v[58:61], v[170:173], v[150:153], v[58:61]
	v_mfma_f32_16x16x32_bf16 v[62:65], v[170:173], v[154:157], v[62:65]
	ds_read_b128 v[214:217], v148 offset:36944
	ds_read_b128 v[198:201], v147 offset:80
	ds_read_b128 v[202:205], v147 offset:2384
	ds_read_b128 v[218:221], v148 offset:39248
	s_waitcnt lgkmcnt(7)
	v_mfma_f32_16x16x32_bf16 v[18:21], v[166:169], v[158:161], v[18:21]
	v_mfma_f32_16x16x32_bf16 v[26:29], v[170:173], v[158:161], v[26:29]
	s_waitcnt lgkmcnt(6)
	v_mfma_f32_16x16x32_bf16 v[22:25], v[166:169], v[162:165], v[22:25]
	v_mfma_f32_16x16x32_bf16 v[30:33], v[170:173], v[162:165], v[30:33]
	ds_read_b128 v[206:209], v147 offset:4688
	ds_read_b128 v[210:213], v147 offset:6992
	ds_read_b128 v[222:225], v148 offset:41552
	ds_read_b128 v[226:229], v148 offset:43856
	s_waitcnt lgkmcnt(9)
	v_mfma_f32_16x16x32_bf16 v[34:37], v[174:177], v[150:153], v[34:37]
	v_mfma_f32_16x16x32_bf16 v[38:41], v[174:177], v[154:157], v[38:41]
	s_waitcnt vmcnt(6)
	ds_write_b128 v144, v[98:101] offset:18448
	ds_write_b128 v144, v[102:105] offset:55312
	v_mfma_f32_16x16x32_bf16 v[2:5], v[174:177], v[158:161], v[2:5]
	v_mfma_f32_16x16x32_bf16 v[6:9], v[174:177], v[162:165], v[6:9]
	s_waitcnt lgkmcnt(10)
	v_mfma_f32_16x16x32_bf16 v[42:45], v[178:181], v[150:153], v[42:45]
	v_mfma_f32_16x16x32_bf16 v[46:49], v[178:181], v[154:157], v[46:49]
	s_waitcnt vmcnt(4)
	ds_write_b128 v144, v[106:109] offset:23056
	ds_write_b128 v144, v[110:113] offset:59920
	v_mfma_f32_16x16x32_bf16 v[10:13], v[178:181], v[158:161], v[10:13]
	v_mfma_f32_16x16x32_bf16 v[14:17], v[178:181], v[162:165], v[14:17]
	s_waitcnt lgkmcnt(10)
	v_mfma_f32_16x16x32_bf16 v[50:53], v[214:217], v[198:201], v[50:53]
	s_waitcnt lgkmcnt(9)
	v_mfma_f32_16x16x32_bf16 v[54:57], v[214:217], v[202:205], v[54:57]
	s_waitcnt vmcnt(2)
	ds_write_b128 v144, v[114:117] offset:27664
	ds_write_b128 v144, v[118:121] offset:64528
	s_waitcnt lgkmcnt(10)
	v_mfma_f32_16x16x32_bf16 v[58:61], v[218:221], v[198:201], v[58:61]
	v_mfma_f32_16x16x32_bf16 v[62:65], v[218:221], v[202:205], v[62:65]
	s_waitcnt lgkmcnt(9)
	v_mfma_f32_16x16x32_bf16 v[18:21], v[214:217], v[206:209], v[18:21]
	v_mfma_f32_16x16x32_bf16 v[26:29], v[218:221], v[206:209], v[26:29]
	s_waitcnt vmcnt(0)
	ds_write_b128 v144, v[122:125] offset:32272
	ds_write_b128 v145, v[126:129] offset:32256
	s_waitcnt lgkmcnt(10)
	v_mfma_f32_16x16x32_bf16 v[22:25], v[214:217], v[210:213], v[22:25]
	v_mfma_f32_16x16x32_bf16 v[30:33], v[218:221], v[210:213], v[30:33]
	s_waitcnt lgkmcnt(9)
	v_mfma_f32_16x16x32_bf16 v[34:37], v[222:225], v[198:201], v[34:37]
	v_mfma_f32_16x16x32_bf16 v[38:41], v[222:225], v[202:205], v[38:41]
	v_mfma_f32_16x16x32_bf16 v[2:5], v[222:225], v[206:209], v[2:5]
	v_mfma_f32_16x16x32_bf16 v[6:9], v[222:225], v[210:213], v[6:9]
	s_waitcnt lgkmcnt(8)
	v_mfma_f32_16x16x32_bf16 v[42:45], v[226:229], v[198:201], v[42:45]
	v_mfma_f32_16x16x32_bf16 v[46:49], v[226:229], v[202:205], v[46:49]
	v_mfma_f32_16x16x32_bf16 v[10:13], v[226:229], v[206:209], v[10:13]
	v_mfma_f32_16x16x32_bf16 v[14:17], v[226:229], v[210:213], v[14:17]
	s_waitcnt lgkmcnt(0)
	s_barrier
; #define MFMA(a, b, c) __builtin_amdgcn_mfma_f32_32x32x16_bf16((a), (b), (c), 0, 0, 0)
; template <bool SWAP, class Epi>
; DI void gemm_tile(const u16* __restrict__ A, int lda, const u16* __restrict__ Bt, int ldb, int K, int m0, int n0, char* smem, Epi&& epi) {
;     ...
;   auto compute = [&](int buf) __attribute__((always_inline)) {
;     bf16x8 af[2][2], bfr[2][2];
;     af[0][0] = *(const bf16x8*)(Asb + buf * 128 * 72);
;     af[0][1] = *(const bf16x8*)(Asb + buf * 128 * 72 + 32 * 72);
;     bfr[0][0] = *(const bf16x8*)(Bsb + buf * 128 * 72);
;     bfr[0][1] = *(const bf16x8*)(Bsb + buf * 128 * 72 + 32 * 72);
; #pragma unroll
;     for (int ks = 0; ks < 4; ++ks) {
;       const int c = ks & 1, n = c ^ 1;
;       if (ks < 3) {
;         af[n][0] = *(const bf16x8*)(Asb + buf * 128 * 72 + (ks + 1) * 16);
;         af[n][1] = *(const bf16x8*)(Asb + buf * 128 * 72 + 32 * 72 + (ks + 1) * 16);
;         bfr[n][0] = *(const bf16x8*)(Bsb + buf * 128 * 72 + (ks + 1) * 16);
;         bfr[n][1] = *(const bf16x8*)(Bsb + buf * 128 * 72 + 32 * 72 + (ks + 1) * 16);
;       }
;       __builtin_amdgcn_sched_barrier(0);
; #pragma unroll
;       for (int mi = 0; mi < 2; ++mi)
; #pragma unroll
;         for (int ni = 0; ni < 2; ++ni) {
;           if (SWAP) acc[mi][ni] = MFMA(bfr[c][ni], af[c][mi], acc[mi][ni]);
;           else acc[mi][ni] = MFMA(af[c][mi], bfr[c][ni], acc[mi][ni]);
;         }
;       __builtin_amdgcn_sched_barrier(0);
;     }
;   };
;     ...
;     compute(1);
;     if (kt + 2 < KT) {
; #pragma unroll
;       for (int i = 0; i < 4; ++i) { *(u32x4*)(asw + 32 * i * 72) = ra0[i]; *(u32x4*)(bsw + 32 * i * 72) = rb0[i]; }
;     }
;     __syncthreads();
	ds_read_b128 v[166:169], v148 offset:55312
	ds_read_b128 v[150:153], v147 offset:18448
	ds_read_b128 v[154:157], v147 offset:20752
	ds_read_b128 v[170:173], v148 offset:57616
	ds_read_b128 v[158:161], v147 offset:23056
	ds_read_b128 v[162:165], v147 offset:25360
	ds_read_b128 v[174:177], v148 offset:59920
	ds_read_b128 v[178:181], v148 offset:62224
	s_waitcnt lgkmcnt(6)
	v_mfma_f32_16x16x32_bf16 v[50:53], v[166:169], v[150:153], v[50:53]
	s_waitcnt lgkmcnt(5)
	v_mfma_f32_16x16x32_bf16 v[54:57], v[166:169], v[154:157], v[54:57]
	s_waitcnt lgkmcnt(4)
	v_mfma_f32_16x16x32_bf16 v[58:61], v[170:173], v[150:153], v[58:61]
	v_mfma_f32_16x16x32_bf16 v[62:65], v[170:173], v[154:157], v[62:65]
	ds_read_b128 v[214:217], v148 offset:55376
	ds_read_b128 v[198:201], v147 offset:18512
	ds_read_b128 v[202:205], v147 offset:20816
	ds_read_b128 v[218:221], v148 offset:57680
	s_waitcnt lgkmcnt(7)
	v_mfma_f32_16x16x32_bf16 v[18:21], v[166:169], v[158:161], v[18:21]
	v_mfma_f32_16x16x32_bf16 v[26:29], v[170:173], v[158:161], v[26:29]
	s_waitcnt lgkmcnt(6)
	v_mfma_f32_16x16x32_bf16 v[22:25], v[166:169], v[162:165], v[22:25]
	v_mfma_f32_16x16x32_bf16 v[30:33], v[170:173], v[162:165], v[30:33]
	ds_read_b128 v[206:209], v147 offset:23120
	ds_read_b128 v[210:213], v147 offset:25424
	ds_read_b128 v[222:225], v148 offset:59984
	ds_read_b128 v[226:229], v148 offset:62288
	s_waitcnt lgkmcnt(9)
	v_mfma_f32_16x16x32_bf16 v[34:37], v[174:177], v[150:153], v[34:37]
	v_mfma_f32_16x16x32_bf16 v[38:41], v[174:177], v[154:157], v[38:41]
	v_mfma_f32_16x16x32_bf16 v[2:5], v[174:177], v[158:161], v[2:5]
	v_mfma_f32_16x16x32_bf16 v[6:9], v[174:177], v[162:165], v[6:9]
	s_waitcnt lgkmcnt(8)
	v_mfma_f32_16x16x32_bf16 v[42:45], v[178:181], v[150:153], v[42:45]
	v_mfma_f32_16x16x32_bf16 v[46:49], v[178:181], v[154:157], v[46:49]
	v_mfma_f32_16x16x32_bf16 v[10:13], v[178:181], v[158:161], v[10:13]
	v_mfma_f32_16x16x32_bf16 v[14:17], v[178:181], v[162:165], v[14:17]
	s_waitcnt lgkmcnt(6)
	v_mfma_f32_16x16x32_bf16 v[50:53], v[214:217], v[198:201], v[50:53]
	s_waitcnt lgkmcnt(5)
	v_mfma_f32_16x16x32_bf16 v[54:57], v[214:217], v[202:205], v[54:57]
	s_waitcnt lgkmcnt(4)
	v_mfma_f32_16x16x32_bf16 v[58:61], v[218:221], v[198:201], v[58:61]
	v_mfma_f32_16x16x32_bf16 v[62:65], v[218:221], v[202:205], v[62:65]
	s_waitcnt lgkmcnt(3)
	v_mfma_f32_16x16x32_bf16 v[18:21], v[214:217], v[206:209], v[18:21]
	v_mfma_f32_16x16x32_bf16 v[26:29], v[218:221], v[206:209], v[26:29]
	s_waitcnt lgkmcnt(2)
	v_mfma_f32_16x16x32_bf16 v[22:25], v[214:217], v[210:213], v[22:25]
	v_mfma_f32_16x16x32_bf16 v[30:33], v[218:221], v[210:213], v[30:33]
	s_waitcnt lgkmcnt(1)
	v_mfma_f32_16x16x32_bf16 v[34:37], v[222:225], v[198:201], v[34:37]
	v_mfma_f32_16x16x32_bf16 v[38:41], v[222:225], v[202:205], v[38:41]
	v_mfma_f32_16x16x32_bf16 v[2:5], v[222:225], v[206:209], v[2:5]
	v_mfma_f32_16x16x32_bf16 v[6:9], v[222:225], v[210:213], v[6:9]
	s_waitcnt lgkmcnt(0)
	v_mfma_f32_16x16x32_bf16 v[42:45], v[226:229], v[198:201], v[42:45]
	v_mfma_f32_16x16x32_bf16 v[46:49], v[226:229], v[202:205], v[46:49]
	v_mfma_f32_16x16x32_bf16 v[10:13], v[226:229], v[206:209], v[10:13]
	v_mfma_f32_16x16x32_bf16 v[14:17], v[226:229], v[210:213], v[14:17]
	s_nop 7
	s_nop 7
	v_permlane16_swap_b32_e32 v50, v54
	v_permlane16_swap_b32_e32 v51, v55
	v_permlane16_swap_b32_e32 v52, v56
	v_permlane16_swap_b32_e32 v53, v57
	v_permlane16_swap_b32_e32 v58, v62
	v_permlane16_swap_b32_e32 v59, v63
	v_permlane16_swap_b32_e32 v60, v64
	v_permlane16_swap_b32_e32 v61, v65
	v_permlane16_swap_b32_e32 v34, v38
	v_permlane16_swap_b32_e32 v35, v39
	v_permlane16_swap_b32_e32 v36, v40
	v_permlane16_swap_b32_e32 v37, v41
	v_permlane16_swap_b32_e32 v42, v46
	v_permlane16_swap_b32_e32 v43, v47
	v_permlane16_swap_b32_e32 v44, v48
	v_permlane16_swap_b32_e32 v45, v49
	v_permlane16_swap_b32_e32 v18, v22
	v_permlane16_swap_b32_e32 v19, v23
	v_permlane16_swap_b32_e32 v20, v24
	v_permlane16_swap_b32_e32 v21, v25
	v_permlane16_swap_b32_e32 v26, v30
	v_permlane16_swap_b32_e32 v27, v31
	v_permlane16_swap_b32_e32 v28, v32
	v_permlane16_swap_b32_e32 v29, v33
	v_permlane16_swap_b32_e32 v2, v6
	v_permlane16_swap_b32_e32 v3, v7
	v_permlane16_swap_b32_e32 v4, v8
	v_permlane16_swap_b32_e32 v5, v9
	v_permlane16_swap_b32_e32 v10, v14
	v_permlane16_swap_b32_e32 v11, v15
	v_permlane16_swap_b32_e32 v12, v16
	v_permlane16_swap_b32_e32 v13, v17
	v_permlane32_swap_b32_e32 v50, v54
	v_permlane32_swap_b32_e32 v51, v55
	v_permlane32_swap_b32_e32 v52, v56
	v_permlane32_swap_b32_e32 v53, v57
	v_permlane32_swap_b32_e32 v58, v62
	v_permlane32_swap_b32_e32 v59, v63
	v_permlane32_swap_b32_e32 v60, v64
	v_permlane32_swap_b32_e32 v61, v65
	v_permlane32_swap_b32_e32 v34, v38
	v_permlane32_swap_b32_e32 v35, v39
	v_permlane32_swap_b32_e32 v36, v40
	v_permlane32_swap_b32_e32 v37, v41
	v_permlane32_swap_b32_e32 v42, v46
	v_permlane32_swap_b32_e32 v43, v47
	v_permlane32_swap_b32_e32 v44, v48
	v_permlane32_swap_b32_e32 v45, v49
	v_permlane32_swap_b32_e32 v18, v22
	v_permlane32_swap_b32_e32 v19, v23
	v_permlane32_swap_b32_e32 v20, v24
	v_permlane32_swap_b32_e32 v21, v25
	v_permlane32_swap_b32_e32 v26, v30
	v_permlane32_swap_b32_e32 v27, v31
	v_permlane32_swap_b32_e32 v28, v32
	v_permlane32_swap_b32_e32 v29, v33
	v_permlane32_swap_b32_e32 v2, v6
	v_permlane32_swap_b32_e32 v3, v7
	v_permlane32_swap_b32_e32 v4, v8
	v_permlane32_swap_b32_e32 v5, v9
	v_permlane32_swap_b32_e32 v10, v14
	v_permlane32_swap_b32_e32 v11, v15
	v_permlane32_swap_b32_e32 v12, v16
	v_permlane32_swap_b32_e32 v13, v17
	s_waitcnt lgkmcnt(0)
	s_barrier
	s_branch .LBB0_745

; #define MFMA(a, b, c) __builtin_amdgcn_mfma_f32_32x32x16_bf16((a), (b), (c), 0, 0, 0)
; template <bool SWAP, class Epi>
; DI void gemm_tile(const u16* __restrict__ A, int lda, const u16* __restrict__ Bt, int ldb, int K, int m0, int n0, char* smem, Epi&& epi) {
;     ...
;   auto compute = [&](int buf) __attribute__((always_inline)) {
;     bf16x8 af[2][2], bfr[2][2];
;     af[0][0] = *(const bf16x8*)(Asb + buf * 128 * 72);
;     af[0][1] = *(const bf16x8*)(Asb + buf * 128 * 72 + 32 * 72);
;     bfr[0][0] = *(const bf16x8*)(Bsb + buf * 128 * 72);
;     bfr[0][1] = *(const bf16x8*)(Bsb + buf * 128 * 72 + 32 * 72);
; #pragma unroll
;     for (int ks = 0; ks < 4; ++ks) {
;       const int c = ks & 1, n = c ^ 1;
;       if (ks < 3) {
;         af[n][0] = *(const bf16x8*)(Asb + buf * 128 * 72 + (ks + 1) * 16);
;         af[n][1] = *(const bf16x8*)(Asb + buf * 128 * 72 + 32 * 72 + (ks + 1) * 16);
;         bfr[n][0] = *(const bf16x8*)(Bsb + buf * 128 * 72 + (ks + 1) * 16);
;         bfr[n][1] = *(const bf16x8*)(Bsb + buf * 128 * 72 + 32 * 72 + (ks + 1) * 16);
;       }
;       __builtin_amdgcn_sched_barrier(0);
; #pragma unroll
;       for (int mi = 0; mi < 2; ++mi)
; #pragma unroll
;         for (int ni = 0; ni < 2; ++ni) {
;           if (SWAP) acc[mi][ni] = MFMA(bfr[c][ni], af[c][mi], acc[mi][ni]);
;           else acc[mi][ni] = MFMA(af[c][mi], bfr[c][ni], acc[mi][ni]);
;         }
;       __builtin_amdgcn_sched_barrier(0);
;     }
;   };
;   for (int kt = 0; kt < KT; kt += 2) {
;     if (kt + 2 < KT) {
;       const int k0 = (kt + 2) << 6;
; #pragma unroll
;       for (int i = 0; i < 4; ++i) { ra0[i] = *(const u32x4*)(ag + (size_t)i * 32 * lda + k0); rb0[i] = *(const u32x4*)(bg + (size_t)i * 32 * ldb + k0); }
;     }
;     compute(0);
; #pragma unroll
;     for (int i = 0; i < 4; ++i) { *(u32x4*)(asw + 128 * 72 + 32 * i * 72) = ra1[i]; *(u32x4*)(bsw + 128 * 72 + 32 * i * 72) = rb1[i]; }
;     __syncthreads();
;     if (kt + 3 < KT) {
;       const int k0 = (kt + 3) << 6;
; #pragma unroll
;       for (int i = 0; i < 4; ++i) { ra1[i] = *(const u32x4*)(ag + (size_t)i * 32 * lda + k0); rb1[i] = *(const u32x4*)(bg + (size_t)i * 32 * ldb + k0); }
;     }
;     compute(1);
.LBB0_955:
	global_load_dwordx4 v[66:69], v194, s[100:101] offset:256
	global_load_dwordx4 v[70:73], v190, s[98:99] offset:256
	global_load_dwordx4 v[74:77], v195, s[100:101] offset:256
	global_load_dwordx4 v[78:81], v191, s[98:99] offset:256
	global_load_dwordx4 v[82:85], v196, s[100:101] offset:256
	global_load_dwordx4 v[86:89], v192, s[98:99] offset:256
	global_load_dwordx4 v[90:93], v197, s[100:101] offset:256
	global_load_dwordx4 v[94:97], v193, s[98:99] offset:256
	ds_read_b128 v[166:169], v148 offset:36880
	ds_read_b128 v[150:153], v147 offset:16
	ds_read_b128 v[154:157], v147 offset:2320
	ds_read_b128 v[170:173], v148 offset:39184
	ds_read_b128 v[158:161], v147 offset:4624
	ds_read_b128 v[162:165], v147 offset:6928
	ds_read_b128 v[174:177], v148 offset:41488
	ds_read_b128 v[178:181], v148 offset:43792
	s_waitcnt lgkmcnt(6)
	v_mfma_f32_16x16x32_bf16 v[50:53], v[166:169], v[150:153], v[50:53]
	s_waitcnt lgkmcnt(5)
	v_mfma_f32_16x16x32_bf16 v[54:57], v[166:169], v[154:157], v[54:57]
	s_waitcnt lgkmcnt(4)
	v_mfma_f32_16x16x32_bf16 v[58:61], v[170:173], v[150:153], v[58:61]
	v_mfma_f32_16x16x32_bf16 v[62:65], v[170:173], v[154:157], v[62:65]
	ds_read_b128 v[214:217], v148 offset:36944
	ds_read_b128 v[198:201], v147 offset:80
	ds_read_b128 v[202:205], v147 offset:2384
	ds_read_b128 v[218:221], v148 offset:39248
	s_waitcnt lgkmcnt(7)
	v_mfma_f32_16x16x32_bf16 v[18:21], v[166:169], v[158:161], v[18:21]
	v_mfma_f32_16x16x32_bf16 v[26:29], v[170:173], v[158:161], v[26:29]
	s_waitcnt lgkmcnt(6)
	v_mfma_f32_16x16x32_bf16 v[22:25], v[166:169], v[162:165], v[22:25]
	v_mfma_f32_16x16x32_bf16 v[30:33], v[170:173], v[162:165], v[30:33]
	ds_read_b128 v[206:209], v147 offset:4688
	ds_read_b128 v[210:213], v147 offset:6992
	ds_read_b128 v[222:225], v148 offset:41552
	ds_read_b128 v[226:229], v148 offset:43856
	s_waitcnt lgkmcnt(9)
	v_mfma_f32_16x16x32_bf16 v[34:37], v[174:177], v[150:153], v[34:37]
	v_mfma_f32_16x16x32_bf16 v[38:41], v[174:177], v[154:157], v[38:41]
	s_waitcnt vmcnt(14)
	ds_write_b128 v144, v[98:101] offset:18448
	ds_write_b128 v144, v[102:105] offset:55312
	v_mfma_f32_16x16x32_bf16 v[2:5], v[174:177], v[158:161], v[2:5]
	v_mfma_f32_16x16x32_bf16 v[6:9], v[174:177], v[162:165], v[6:9]
	s_waitcnt lgkmcnt(10)
	v_mfma_f32_16x16x32_bf16 v[42:45], v[178:181], v[150:153], v[42:45]
	v_mfma_f32_16x16x32_bf16 v[46:49], v[178:181], v[154:157], v[46:49]
	s_waitcnt vmcnt(12)
	ds_write_b128 v144, v[106:109] offset:23056
	ds_write_b128 v144, v[110:113] offset:59920
	v_mfma_f32_16x16x32_bf16 v[10:13], v[178:181], v[158:161], v[10:13]
	v_mfma_f32_16x16x32_bf16 v[14:17], v[178:181], v[162:165], v[14:17]
	s_waitcnt lgkmcnt(10)
	v_mfma_f32_16x16x32_bf16 v[50:53], v[214:217], v[198:201], v[50:53]
	s_waitcnt lgkmcnt(9)
	v_mfma_f32_16x16x32_bf16 v[54:57], v[214:217], v[202:205], v[54:57]
	s_waitcnt vmcnt(10)
	ds_write_b128 v144, v[114:117] offset:27664
	ds_write_b128 v144, v[118:121] offset:64528
	s_waitcnt lgkmcnt(10)
	v_mfma_f32_16x16x32_bf16 v[58:61], v[218:221], v[198:201], v[58:61]
	v_mfma_f32_16x16x32_bf16 v[62:65], v[218:221], v[202:205], v[62:65]
	s_waitcnt lgkmcnt(9)
	v_mfma_f32_16x16x32_bf16 v[18:21], v[214:217], v[206:209], v[18:21]
	v_mfma_f32_16x16x32_bf16 v[26:29], v[218:221], v[206:209], v[26:29]
	s_waitcnt vmcnt(8)
	ds_write_b128 v144, v[122:125] offset:32272
	ds_write_b128 v145, v[126:129] offset:32256
	s_waitcnt lgkmcnt(10)
	v_mfma_f32_16x16x32_bf16 v[22:25], v[214:217], v[210:213], v[22:25]
	v_mfma_f32_16x16x32_bf16 v[30:33], v[218:221], v[210:213], v[30:33]
	s_waitcnt lgkmcnt(9)
	v_mfma_f32_16x16x32_bf16 v[34:37], v[222:225], v[198:201], v[34:37]
	v_mfma_f32_16x16x32_bf16 v[38:41], v[222:225], v[202:205], v[38:41]
	v_mfma_f32_16x16x32_bf16 v[2:5], v[222:225], v[206:209], v[2:5]
	v_mfma_f32_16x16x32_bf16 v[6:9], v[222:225], v[210:213], v[6:9]
	s_waitcnt lgkmcnt(8)
	v_mfma_f32_16x16x32_bf16 v[42:45], v[226:229], v[198:201], v[42:45]
	v_mfma_f32_16x16x32_bf16 v[46:49], v[226:229], v[202:205], v[46:49]
	v_mfma_f32_16x16x32_bf16 v[10:13], v[226:229], v[206:209], v[10:13]
	v_mfma_f32_16x16x32_bf16 v[14:17], v[226:229], v[210:213], v[14:17]
	s_waitcnt lgkmcnt(0)
	s_barrier
	global_load_dwordx4 v[98:101], v194, s[100:101] offset:384
	global_load_dwordx4 v[102:105], v190, s[98:99] offset:384
	global_load_dwordx4 v[106:109], v195, s[100:101] offset:384
	global_load_dwordx4 v[110:113], v191, s[98:99] offset:384
	global_load_dwordx4 v[114:117], v196, s[100:101] offset:384
	global_load_dwordx4 v[118:121], v192, s[98:99] offset:384
	global_load_dwordx4 v[122:125], v197, s[100:101] offset:384
	global_load_dwordx4 v[126:129], v193, s[98:99] offset:384
	ds_read_b128 v[166:169], v148 offset:55312
	ds_read_b128 v[150:153], v147 offset:18448
	ds_read_b128 v[154:157], v147 offset:20752
	ds_read_b128 v[170:173], v148 offset:57616
	ds_read_b128 v[158:161], v147 offset:23056
	ds_read_b128 v[162:165], v147 offset:25360
	ds_read_b128 v[174:177], v148 offset:59920
	ds_read_b128 v[178:181], v148 offset:62224
	s_waitcnt lgkmcnt(6)
	v_mfma_f32_16x16x32_bf16 v[50:53], v[166:169], v[150:153], v[50:53]
	s_waitcnt lgkmcnt(5)
	v_mfma_f32_16x16x32_bf16 v[54:57], v[166:169], v[154:157], v[54:57]
	s_waitcnt lgkmcnt(4)
	v_mfma_f32_16x16x32_bf16 v[58:61], v[170:173], v[150:153], v[58:61]
	v_mfma_f32_16x16x32_bf16 v[62:65], v[170:173], v[154:157], v[62:65]
	ds_read_b128 v[214:217], v148 offset:55376
	ds_read_b128 v[198:201], v147 offset:18512
	ds_read_b128 v[202:205], v147 offset:20816
	ds_read_b128 v[218:221], v148 offset:57680
	s_waitcnt lgkmcnt(7)
	v_mfma_f32_16x16x32_bf16 v[18:21], v[166:169], v[158:161], v[18:21]
	v_mfma_f32_16x16x32_bf16 v[26:29], v[170:173], v[158:161], v[26:29]
	s_waitcnt lgkmcnt(6)
; #define MFMA(a, b, c) __builtin_amdgcn_mfma_f32_32x32x16_bf16((a), (b), (c), 0, 0, 0)
; template <bool SWAP, class Epi>
; DI void gemm_tile(const u16* __restrict__ A, int lda, const u16* __restrict__ Bt, int ldb, int K, int m0, int n0, char* smem, Epi&& epi) {
;     ...
;   auto compute = [&](int buf) __attribute__((always_inline)) {
;     bf16x8 af[2][2], bfr[2][2];
;     af[0][0] = *(const bf16x8*)(Asb + buf * 128 * 72);
;     af[0][1] = *(const bf16x8*)(Asb + buf * 128 * 72 + 32 * 72);
;     bfr[0][0] = *(const bf16x8*)(Bsb + buf * 128 * 72);
;     bfr[0][1] = *(const bf16x8*)(Bsb + buf * 128 * 72 + 32 * 72);
; #pragma unroll
;     for (int ks = 0; ks < 4; ++ks) {
;       const int c = ks & 1, n = c ^ 1;
;       if (ks < 3) {
;         af[n][0] = *(const bf16x8*)(Asb + buf * 128 * 72 + (ks + 1) * 16);
;         af[n][1] = *(const bf16x8*)(Asb + buf * 128 * 72 + 32 * 72 + (ks + 1) * 16);
;         bfr[n][0] = *(const bf16x8*)(Bsb + buf * 128 * 72 + (ks + 1) * 16);
;         bfr[n][1] = *(const bf16x8*)(Bsb + buf * 128 * 72 + 32 * 72 + (ks + 1) * 16);
;       }
;       __builtin_amdgcn_sched_barrier(0);
; #pragma unroll
;       for (int mi = 0; mi < 2; ++mi)
; #pragma unroll
;         for (int ni = 0; ni < 2; ++ni) {
;           if (SWAP) acc[mi][ni] = MFMA(bfr[c][ni], af[c][mi], acc[mi][ni]);
;           else acc[mi][ni] = MFMA(af[c][mi], bfr[c][ni], acc[mi][ni]);
;         }
;       __builtin_amdgcn_sched_barrier(0);
;     }
;   };
;   for (int kt = 0; kt < KT; kt += 2) {
;     if (kt + 2 < KT) {
;       const int k0 = (kt + 2) << 6;
; #pragma unroll
;       for (int i = 0; i < 4; ++i) { ra0[i] = *(const u32x4*)(ag + (size_t)i * 32 * lda + k0); rb0[i] = *(const u32x4*)(bg + (size_t)i * 32 * ldb + k0); }
;     }
;     compute(0);
; #pragma unroll
;     for (int i = 0; i < 4; ++i) { *(u32x4*)(asw + 128 * 72 + 32 * i * 72) = ra1[i]; *(u32x4*)(bsw + 128 * 72 + 32 * i * 72) = rb1[i]; }
;     __syncthreads();
;     if (kt + 3 < KT) {
;       const int k0 = (kt + 3) << 6;
; #pragma unroll
;       for (int i = 0; i < 4; ++i) { ra1[i] = *(const u32x4*)(ag + (size_t)i * 32 * lda + k0); rb1[i] = *(const u32x4*)(bg + (size_t)i * 32 * ldb + k0); }
;     }
;     compute(1);
;     if (kt + 2 < KT) {
; #pragma unroll
;       for (int i = 0; i < 4; ++i) { *(u32x4*)(asw + 32 * i * 72) = ra0[i]; *(u32x4*)(bsw + 32 * i * 72) = rb0[i]; }
;     }
;     __syncthreads();
;   }
	v_mfma_f32_16x16x32_bf16 v[22:25], v[166:169], v[162:165], v[22:25]
	v_mfma_f32_16x16x32_bf16 v[30:33], v[170:173], v[162:165], v[30:33]
	ds_read_b128 v[206:209], v147 offset:23120
	ds_read_b128 v[210:213], v147 offset:25424
	ds_read_b128 v[222:225], v148 offset:59984
	ds_read_b128 v[226:229], v148 offset:62288
	s_waitcnt lgkmcnt(9)
	v_mfma_f32_16x16x32_bf16 v[34:37], v[174:177], v[150:153], v[34:37]
	v_mfma_f32_16x16x32_bf16 v[38:41], v[174:177], v[154:157], v[38:41]
	s_waitcnt vmcnt(14)
	ds_write_b128 v144, v[66:69] offset:16
	ds_write_b128 v144, v[70:73] offset:36880
	v_mfma_f32_16x16x32_bf16 v[2:5], v[174:177], v[158:161], v[2:5]
	v_mfma_f32_16x16x32_bf16 v[6:9], v[174:177], v[162:165], v[6:9]
	s_waitcnt lgkmcnt(10)
	v_mfma_f32_16x16x32_bf16 v[42:45], v[178:181], v[150:153], v[42:45]
	v_mfma_f32_16x16x32_bf16 v[46:49], v[178:181], v[154:157], v[46:49]
	s_waitcnt vmcnt(12)
	ds_write_b128 v144, v[74:77] offset:4624
	ds_write_b128 v144, v[78:81] offset:41488
	v_mfma_f32_16x16x32_bf16 v[10:13], v[178:181], v[158:161], v[10:13]
	v_mfma_f32_16x16x32_bf16 v[14:17], v[178:181], v[162:165], v[14:17]
	s_waitcnt lgkmcnt(10)
	v_mfma_f32_16x16x32_bf16 v[50:53], v[214:217], v[198:201], v[50:53]
	s_waitcnt lgkmcnt(9)
	v_mfma_f32_16x16x32_bf16 v[54:57], v[214:217], v[202:205], v[54:57]
	s_waitcnt vmcnt(10)
	ds_write_b128 v144, v[82:85] offset:9232
	ds_write_b128 v144, v[86:89] offset:46096
	s_waitcnt lgkmcnt(10)
	v_mfma_f32_16x16x32_bf16 v[58:61], v[218:221], v[198:201], v[58:61]
	v_mfma_f32_16x16x32_bf16 v[62:65], v[218:221], v[202:205], v[62:65]
	s_waitcnt lgkmcnt(9)
	v_mfma_f32_16x16x32_bf16 v[18:21], v[214:217], v[206:209], v[18:21]
	v_mfma_f32_16x16x32_bf16 v[26:29], v[218:221], v[206:209], v[26:29]
	s_waitcnt vmcnt(8)
	ds_write_b128 v144, v[90:93] offset:13840
	ds_write_b128 v144, v[94:97] offset:50704
	s_waitcnt lgkmcnt(10)
	v_mfma_f32_16x16x32_bf16 v[22:25], v[214:217], v[210:213], v[22:25]
	v_mfma_f32_16x16x32_bf16 v[30:33], v[218:221], v[210:213], v[30:33]
	s_waitcnt lgkmcnt(9)
	v_mfma_f32_16x16x32_bf16 v[34:37], v[222:225], v[198:201], v[34:37]
	v_mfma_f32_16x16x32_bf16 v[38:41], v[222:225], v[202:205], v[38:41]
	v_mfma_f32_16x16x32_bf16 v[2:5], v[222:225], v[206:209], v[2:5]
	v_mfma_f32_16x16x32_bf16 v[6:9], v[222:225], v[210:213], v[6:9]
	s_waitcnt lgkmcnt(8)
	v_mfma_f32_16x16x32_bf16 v[42:45], v[226:229], v[198:201], v[42:45]
	v_mfma_f32_16x16x32_bf16 v[46:49], v[226:229], v[202:205], v[46:49]
	v_mfma_f32_16x16x32_bf16 v[10:13], v[226:229], v[206:209], v[10:13]
	v_mfma_f32_16x16x32_bf16 v[14:17], v[226:229], v[210:213], v[14:17]
	s_add_i32 s18, s18, 2
	s_add_u32 s98, s98, 256
	s_addc_u32 s99, s99, 0
	s_add_u32 s100, s100, 256
	s_addc_u32 s101, s101, 0
	s_waitcnt lgkmcnt(0)
	s_barrier
	s_cmp_lt_u32 s18, 30
	s_cbranch_scc1 .LBB0_955
	ds_read_b128 v[166:169], v148 offset:36880
	ds_read_b128 v[150:153], v147 offset:16
	ds_read_b128 v[154:157], v147 offset:2320
	ds_read_b128 v[170:173], v148 offset:39184
	ds_read_b128 v[158:161], v147 offset:4624
	ds_read_b128 v[162:165], v147 offset:6928
	ds_read_b128 v[174:177], v148 offset:41488
	ds_read_b128 v[178:181], v148 offset:43792
	s_waitcnt lgkmcnt(6)
	v_mfma_f32_16x16x32_bf16 v[50:53], v[166:169], v[150:153], v[50:53]
	s_waitcnt lgkmcnt(5)
	v_mfma_f32_16x16x32_bf16 v[54:57], v[166:169], v[154:157], v[54:57]
	s_waitcnt lgkmcnt(4)
	v_mfma_f32_16x16x32_bf16 v[58:61], v[170:173], v[150:153], v[58:61]
	v_mfma_f32_16x16x32_bf16 v[62:65], v[170:173], v[154:157], v[62:65]
	ds_read_b128 v[214:217], v148 offset:36944
	ds_read_b128 v[198:201], v147 offset:80
	ds_read_b128 v[202:205], v147 offset:2384
	ds_read_b128 v[218:221], v148 offset:39248
	s_waitcnt lgkmcnt(7)
	v_mfma_f32_16x16x32_bf16 v[18:21], v[166:169], v[158:161], v[18:21]
	v_mfma_f32_16x16x32_bf16 v[26:29], v[170:173], v[158:161], v[26:29]
	s_waitcnt lgkmcnt(6)
	v_mfma_f32_16x16x32_bf16 v[22:25], v[166:169], v[162:165], v[22:25]
	v_mfma_f32_16x16x32_bf16 v[30:33], v[170:173], v[162:165], v[30:33]
	ds_read_b128 v[206:209], v147 offset:4688
	ds_read_b128 v[210:213], v147 offset:6992
	ds_read_b128 v[222:225], v148 offset:41552
	ds_read_b128 v[226:229], v148 offset:43856
	s_waitcnt lgkmcnt(9)
	v_mfma_f32_16x16x32_bf16 v[34:37], v[174:177], v[150:153], v[34:37]
	v_mfma_f32_16x16x32_bf16 v[38:41], v[174:177], v[154:157], v[38:41]
	s_waitcnt vmcnt(6)
	ds_write_b128 v144, v[98:101] offset:18448
	ds_write_b128 v144, v[102:105] offset:55312
	v_mfma_f32_16x16x32_bf16 v[2:5], v[174:177], v[158:161], v[2:5]
	v_mfma_f32_16x16x32_bf16 v[6:9], v[174:177], v[162:165], v[6:9]
	s_waitcnt lgkmcnt(10)
	v_mfma_f32_16x16x32_bf16 v[42:45], v[178:181], v[150:153], v[42:45]
	v_mfma_f32_16x16x32_bf16 v[46:49], v[178:181], v[154:157], v[46:49]
	s_waitcnt vmcnt(4)
	ds_write_b128 v144, v[106:109] offset:23056
	ds_write_b128 v144, v[110:113] offset:59920
	v_mfma_f32_16x16x32_bf16 v[10:13], v[178:181], v[158:161], v[10:13]
	v_mfma_f32_16x16x32_bf16 v[14:17], v[178:181], v[162:165], v[14:17]
	s_waitcnt lgkmcnt(10)
	v_mfma_f32_16x16x32_bf16 v[50:53], v[214:217], v[198:201], v[50:53]
	s_waitcnt lgkmcnt(9)
	v_mfma_f32_16x16x32_bf16 v[54:57], v[214:217], v[202:205], v[54:57]
	s_waitcnt vmcnt(2)
	ds_write_b128 v144, v[114:117] offset:27664
	ds_write_b128 v144, v[118:121] offset:64528
	s_waitcnt lgkmcnt(10)
	v_mfma_f32_16x16x32_bf16 v[58:61], v[218:221], v[198:201], v[58:61]
	v_mfma_f32_16x16x32_bf16 v[62:65], v[218:221], v[202:205], v[62:65]
	s_waitcnt lgkmcnt(9)
	v_mfma_f32_16x16x32_bf16 v[18:21], v[214:217], v[206:209], v[18:21]
	v_mfma_f32_16x16x32_bf16 v[26:29], v[218:221], v[206:209], v[26:29]
	s_waitcnt vmcnt(0)
	ds_write_b128 v144, v[122:125] offset:32272
	ds_write_b128 v145, v[126:129] offset:32256
	s_waitcnt lgkmcnt(10)
	v_mfma_f32_16x16x32_bf16 v[22:25], v[214:217], v[210:213], v[22:25]
	v_mfma_f32_16x16x32_bf16 v[30:33], v[218:221], v[210:213], v[30:33]
	s_waitcnt lgkmcnt(9)
	v_mfma_f32_16x16x32_bf16 v[34:37], v[222:225], v[198:201], v[34:37]
	v_mfma_f32_16x16x32_bf16 v[38:41], v[222:225], v[202:205], v[38:41]
	v_mfma_f32_16x16x32_bf16 v[2:5], v[222:225], v[206:209], v[2:5]
	v_mfma_f32_16x16x32_bf16 v[6:9], v[222:225], v[210:213], v[6:9]
	s_waitcnt lgkmcnt(8)
	v_mfma_f32_16x16x32_bf16 v[42:45], v[226:229], v[198:201], v[42:45]
	v_mfma_f32_16x16x32_bf16 v[46:49], v[226:229], v[202:205], v[46:49]
	v_mfma_f32_16x16x32_bf16 v[10:13], v[226:229], v[206:209], v[10:13]
	v_mfma_f32_16x16x32_bf16 v[14:17], v[226:229], v[210:213], v[14:17]
	s_waitcnt lgkmcnt(0)
	s_barrier
; #define MFMA(a, b, c) __builtin_amdgcn_mfma_f32_32x32x16_bf16((a), (b), (c), 0, 0, 0)
; template <bool SWAP, class Epi>
; DI void gemm_tile(const u16* __restrict__ A, int lda, const u16* __restrict__ Bt, int ldb, int K, int m0, int n0, char* smem, Epi&& epi) {
;     ...
;   auto compute = [&](int buf) __attribute__((always_inline)) {
;     bf16x8 af[2][2], bfr[2][2];
;     af[0][0] = *(const bf16x8*)(Asb + buf * 128 * 72);
;     af[0][1] = *(const bf16x8*)(Asb + buf * 128 * 72 + 32 * 72);
;     bfr[0][0] = *(const bf16x8*)(Bsb + buf * 128 * 72);
;     bfr[0][1] = *(const bf16x8*)(Bsb + buf * 128 * 72 + 32 * 72);
; #pragma unroll
;     for (int ks = 0; ks < 4; ++ks) {
;       const int c = ks & 1, n = c ^ 1;
;       if (ks < 3) {
;         af[n][0] = *(const bf16x8*)(Asb + buf * 128 * 72 + (ks + 1) * 16);
;         af[n][1] = *(const bf16x8*)(Asb + buf * 128 * 72 + 32 * 72 + (ks + 1) * 16);
;         bfr[n][0] = *(const bf16x8*)(Bsb + buf * 128 * 72 + (ks + 1) * 16);
;         bfr[n][1] = *(const bf16x8*)(Bsb + buf * 128 * 72 + 32 * 72 + (ks + 1) * 16);
;       }
;       __builtin_amdgcn_sched_barrier(0);
; #pragma unroll
;       for (int mi = 0; mi < 2; ++mi)
; #pragma unroll
;         for (int ni = 0; ni < 2; ++ni) {
;           if (SWAP) acc[mi][ni] = MFMA(bfr[c][ni], af[c][mi], acc[mi][ni]);
;           else acc[mi][ni] = MFMA(af[c][mi], bfr[c][ni], acc[mi][ni]);
;         }
;       __builtin_amdgcn_sched_barrier(0);
;     }
;   };
;     ...
;     compute(1);
;     if (kt + 2 < KT) {
; #pragma unroll
;       for (int i = 0; i < 4; ++i) { *(u32x4*)(asw + 32 * i * 72) = ra0[i]; *(u32x4*)(bsw + 32 * i * 72) = rb0[i]; }
;     }
;     __syncthreads();
	ds_read_b128 v[166:169], v148 offset:55312
	ds_read_b128 v[150:153], v147 offset:18448
	ds_read_b128 v[154:157], v147 offset:20752
	ds_read_b128 v[170:173], v148 offset:57616
	ds_read_b128 v[158:161], v147 offset:23056
	ds_read_b128 v[162:165], v147 offset:25360
	ds_read_b128 v[174:177], v148 offset:59920
	ds_read_b128 v[178:181], v148 offset:62224
	s_waitcnt lgkmcnt(6)
	v_mfma_f32_16x16x32_bf16 v[50:53], v[166:169], v[150:153], v[50:53]
	s_waitcnt lgkmcnt(5)
	v_mfma_f32_16x16x32_bf16 v[54:57], v[166:169], v[154:157], v[54:57]
	s_waitcnt lgkmcnt(4)
	v_mfma_f32_16x16x32_bf16 v[58:61], v[170:173], v[150:153], v[58:61]
	v_mfma_f32_16x16x32_bf16 v[62:65], v[170:173], v[154:157], v[62:65]
	ds_read_b128 v[214:217], v148 offset:55376
	ds_read_b128 v[198:201], v147 offset:18512
	ds_read_b128 v[202:205], v147 offset:20816
	ds_read_b128 v[218:221], v148 offset:57680
	s_waitcnt lgkmcnt(7)
	v_mfma_f32_16x16x32_bf16 v[18:21], v[166:169], v[158:161], v[18:21]
	v_mfma_f32_16x16x32_bf16 v[26:29], v[170:173], v[158:161], v[26:29]
	s_waitcnt lgkmcnt(6)
	v_mfma_f32_16x16x32_bf16 v[22:25], v[166:169], v[162:165], v[22:25]
	v_mfma_f32_16x16x32_bf16 v[30:33], v[170:173], v[162:165], v[30:33]
	ds_read_b128 v[206:209], v147 offset:23120
	ds_read_b128 v[210:213], v147 offset:25424
	ds_read_b128 v[222:225], v148 offset:59984
	ds_read_b128 v[226:229], v148 offset:62288
	s_waitcnt lgkmcnt(9)
	v_mfma_f32_16x16x32_bf16 v[34:37], v[174:177], v[150:153], v[34:37]
	v_mfma_f32_16x16x32_bf16 v[38:41], v[174:177], v[154:157], v[38:41]
	v_mfma_f32_16x16x32_bf16 v[2:5], v[174:177], v[158:161], v[2:5]
	v_mfma_f32_16x16x32_bf16 v[6:9], v[174:177], v[162:165], v[6:9]
	s_waitcnt lgkmcnt(8)
	v_mfma_f32_16x16x32_bf16 v[42:45], v[178:181], v[150:153], v[42:45]
	v_mfma_f32_16x16x32_bf16 v[46:49], v[178:181], v[154:157], v[46:49]
	v_mfma_f32_16x16x32_bf16 v[10:13], v[178:181], v[158:161], v[10:13]
	v_mfma_f32_16x16x32_bf16 v[14:17], v[178:181], v[162:165], v[14:17]
	s_waitcnt lgkmcnt(6)
	v_mfma_f32_16x16x32_bf16 v[50:53], v[214:217], v[198:201], v[50:53]
	s_waitcnt lgkmcnt(5)
	v_mfma_f32_16x16x32_bf16 v[54:57], v[214:217], v[202:205], v[54:57]
	s_waitcnt lgkmcnt(4)
	v_mfma_f32_16x16x32_bf16 v[58:61], v[218:221], v[198:201], v[58:61]
	v_mfma_f32_16x16x32_bf16 v[62:65], v[218:221], v[202:205], v[62:65]
	s_waitcnt lgkmcnt(3)
	v_mfma_f32_16x16x32_bf16 v[18:21], v[214:217], v[206:209], v[18:21]
	v_mfma_f32_16x16x32_bf16 v[26:29], v[218:221], v[206:209], v[26:29]
	s_waitcnt lgkmcnt(2)
	v_mfma_f32_16x16x32_bf16 v[22:25], v[214:217], v[210:213], v[22:25]
	v_mfma_f32_16x16x32_bf16 v[30:33], v[218:221], v[210:213], v[30:33]
	s_waitcnt lgkmcnt(1)
	v_mfma_f32_16x16x32_bf16 v[34:37], v[222:225], v[198:201], v[34:37]
	v_mfma_f32_16x16x32_bf16 v[38:41], v[222:225], v[202:205], v[38:41]
	v_mfma_f32_16x16x32_bf16 v[2:5], v[222:225], v[206:209], v[2:5]
	v_mfma_f32_16x16x32_bf16 v[6:9], v[222:225], v[210:213], v[6:9]
	s_waitcnt lgkmcnt(0)
	v_mfma_f32_16x16x32_bf16 v[42:45], v[226:229], v[198:201], v[42:45]
	v_mfma_f32_16x16x32_bf16 v[46:49], v[226:229], v[202:205], v[46:49]
	v_mfma_f32_16x16x32_bf16 v[10:13], v[226:229], v[206:209], v[10:13]
	v_mfma_f32_16x16x32_bf16 v[14:17], v[226:229], v[210:213], v[14:17]
	s_nop 7
	s_nop 7
	v_permlane16_swap_b32_e32 v50, v54
	v_permlane16_swap_b32_e32 v51, v55
	v_permlane16_swap_b32_e32 v52, v56
	v_permlane16_swap_b32_e32 v53, v57
	v_permlane16_swap_b32_e32 v58, v62
	v_permlane16_swap_b32_e32 v59, v63
	v_permlane16_swap_b32_e32 v60, v64
	v_permlane16_swap_b32_e32 v61, v65
	v_permlane16_swap_b32_e32 v34, v38
	v_permlane16_swap_b32_e32 v35, v39
	v_permlane16_swap_b32_e32 v36, v40
	v_permlane16_swap_b32_e32 v37, v41
	v_permlane16_swap_b32_e32 v42, v46
	v_permlane16_swap_b32_e32 v43, v47
	v_permlane16_swap_b32_e32 v44, v48
	v_permlane16_swap_b32_e32 v45, v49
	v_permlane16_swap_b32_e32 v18, v22
	v_permlane16_swap_b32_e32 v19, v23
	v_permlane16_swap_b32_e32 v20, v24
	v_permlane16_swap_b32_e32 v21, v25
	v_permlane16_swap_b32_e32 v26, v30
	v_permlane16_swap_b32_e32 v27, v31
	v_permlane16_swap_b32_e32 v28, v32
	v_permlane16_swap_b32_e32 v29, v33
	v_permlane16_swap_b32_e32 v2, v6
	v_permlane16_swap_b32_e32 v3, v7
	v_permlane16_swap_b32_e32 v4, v8
	v_permlane16_swap_b32_e32 v5, v9
	v_permlane16_swap_b32_e32 v10, v14
	v_permlane16_swap_b32_e32 v11, v15
	v_permlane16_swap_b32_e32 v12, v16
	v_permlane16_swap_b32_e32 v13, v17
	v_permlane32_swap_b32_e32 v50, v54
	v_permlane32_swap_b32_e32 v51, v55
	v_permlane32_swap_b32_e32 v52, v56
	v_permlane32_swap_b32_e32 v53, v57
	v_permlane32_swap_b32_e32 v58, v62
	v_permlane32_swap_b32_e32 v59, v63
	v_permlane32_swap_b32_e32 v60, v64
	v_permlane32_swap_b32_e32 v61, v65
	v_permlane32_swap_b32_e32 v34, v38
	v_permlane32_swap_b32_e32 v35, v39
	v_permlane32_swap_b32_e32 v36, v40
	v_permlane32_swap_b32_e32 v37, v41
	v_permlane32_swap_b32_e32 v42, v46
	v_permlane32_swap_b32_e32 v43, v47
	v_permlane32_swap_b32_e32 v44, v48
	v_permlane32_swap_b32_e32 v45, v49
	v_permlane32_swap_b32_e32 v18, v22
	v_permlane32_swap_b32_e32 v19, v23
	v_permlane32_swap_b32_e32 v20, v24
	v_permlane32_swap_b32_e32 v21, v25
	v_permlane32_swap_b32_e32 v26, v30
	v_permlane32_swap_b32_e32 v27, v31
	v_permlane32_swap_b32_e32 v28, v32
	v_permlane32_swap_b32_e32 v29, v33
	v_permlane32_swap_b32_e32 v2, v6
	v_permlane32_swap_b32_e32 v3, v7
	v_permlane32_swap_b32_e32 v4, v8
	v_permlane32_swap_b32_e32 v5, v9
	v_permlane32_swap_b32_e32 v10, v14
	v_permlane32_swap_b32_e32 v11, v15
	v_permlane32_swap_b32_e32 v12, v16
	v_permlane32_swap_b32_e32 v13, v17
	s_waitcnt lgkmcnt(0)
	s_barrier
	s_branch .LBB0_952
